# SSM pass 1: the 32 E^T weight fragments kept register-resident for the whole item instead of re-read from LDS (with a full wait) in front of every MFMA
# speedup vs baseline: 1.0043x; 1.0043x over previous
; #define LAS __attribute__((address_space(3)))
; template <bool PASS2>
; __device__ __forceinline__ void ssm_phase(const Params& p, const Frame& F0) {
;     ...
;         const LAS bf16x8* frag = (const LAS bf16x8*)F.lds + lane;
;         const LAS f32x4* m1t = (const LAS f32x4*)(F.lds + SSM_M1_OFF) + 2 * gq;
;         const int b = subset >> 2, wch = (subset & 3) * 8 + F.wave;
;         f32x4 xs[8];
; #pragma unroll
;         for (int i = 0; i < 8; ++i) xs[i] = (f32x4){0.f, 0.f, 0.f, 0.f};
;     ...
;         for (int cc = 0; cc < nch; ++cc) {
;             asm volatile("" ::: "memory");
;             const bool samp = (cc == 4);
;             const int row0 = SSM_ROW0(cc), nsub = SSM_NSUB(cc), js = jsamp;
;             if (samp) {
; #pragma unroll
;                 for (int i = 0; i < 4; ++i) { xs[i] = *(const f32x4*)(p.in[2] + (size_t)(js * NG + g) * 64 + 16 * i + 4 * gq); xs[i + 4] = *(const f32x4*)(p.in[3] + (size_t)(js * NG + g) * 64 + 16 * i + 4 * gq); } }
;             if (cc + 1 < nch) SSM_LOAD_U(ufn, uwn, cc + 1)
;             unsigned hw[4][4];
; #pragma unroll
;             for (int i = 0; i < 4; ++i) {
;                 __builtin_amdgcn_sched_barrier(0);
;                 f32x4 Er = (f32x4){0.f, 0.f, 0.f, 0.f}, Ei = Er;
; #pragma unroll
;                 for (int ks = 0; ks < 4; ++ks) { Er = __builtin_amdgcn_mfma_f32_16x16x32_bf16(frag[(i * 4 + ks) * 64], uf[ks], Er, 0, 0, 0);
;                                                  Ei = __builtin_amdgcn_mfma_f32_16x16x32_bf16(frag[((i + 4) * 4 + ks) * 64], uf[ks], Ei, 0, 0, 0); }
;                 const f32x4 ma = m1t[8 * i], mb = m1t[8 * i + 1];
;                 float mr[4] = {ma[0], ma[2], mb[0], mb[2]}, mi[4] = {ma[1], ma[3], mb[1], mb[3]};
;                 float hr[4], hi[4];
; #pragma unroll
;                 for (int r = 0; r < 4; ++r) { hr[r] = dppf<DPP_ROR(1)>(xs[i][r]); hi[r] = dppf<DPP_ROR(1)>(xs[i + 4][r]);
;                     if (j == 0) { Er[r] += mr[r] * hr[r] - mi[r] * hi[r]; Ei[r] += mr[r] * hi[r] + mi[r] * hr[r]; } }
.LBB0_526:
	s_or_b64 exec, exec, s[0:1]
	s_lshr_b32 s0, s23, 2
	s_and_b32 s18, s0, 24
	s_ashr_i32 s17, s23, 7
	s_add_i32 s18, s18, s3
	s_lshl_b32 s0, s17, 14
	s_lshl_b32 s1, s18, 9
	s_add_i32 s1, s1, s0
	v_or_b32_e32 v0, s1, v106
	v_or_b32_e32 v4, 2, v0
	s_lshl_b32 s10, s16, 5
	v_ashrrev_i32_e32 v1, 31, v0
	v_ashrrev_i32_e32 v5, 31, v4
	v_lshl_add_u64 v[64:65], v[38:39], 0, s[10:11]
	v_lshlrev_b64 v[2:3], 10, v[0:1]
	v_lshlrev_b64 v[4:5], 10, v[4:5]
	v_lshl_add_u64 v[2:3], v[64:65], 0, v[2:3]
	v_lshl_add_u64 v[4:5], v[64:65], 0, v[4:5]
	s_waitcnt lgkmcnt(0)
	s_barrier
	global_load_dwordx4 v[12:15], v[2:3], off
	s_nop 0
	global_load_dwordx4 v[4:7], v[4:5], off
	v_or_b32_e32 v2, 4, v0
	v_or_b32_e32 v0, 6, v0
	v_ashrrev_i32_e32 v3, 31, v2
	v_ashrrev_i32_e32 v1, 31, v0
	v_lshlrev_b64 v[2:3], 10, v[2:3]
	v_lshlrev_b64 v[0:1], 10, v[0:1]
	v_lshl_add_u64 v[2:3], v[64:65], 0, v[2:3]
	v_lshl_add_u64 v[0:1], v[64:65], 0, v[0:1]
	global_load_dwordx4 v[8:11], v[2:3], off
	s_nop 0
	global_load_dwordx4 v[0:3], v[0:1], off
	s_lshl_b32 s1, s23, 7
	s_and_b32 s1, s1, 0x3000
	s_or_b32 s0, s1, s0
	v_add_u32_e32 v80, s0, v37
	s_mov_b32 s0, 0
	v_mov_b32_e32 v44, 0
	v_mov_b32_e32 v45, 0
	v_mov_b32_e32 v48, 0
	v_mov_b32_e32 v49, 0
	v_mov_b32_e32 v52, 0
	v_mov_b32_e32 v53, 0
	v_mov_b32_e32 v56, 0
	v_mov_b32_e32 v57, 0
	v_mov_b32_e32 v60, 0
	v_mov_b32_e32 v61, 0
	v_mov_b32_e32 v66, 0
	v_mov_b32_e32 v67, 0
	v_mov_b32_e32 v70, 0
	v_mov_b32_e32 v71, 0
	v_mov_b32_e32 v74, 0
	v_mov_b32_e32 v75, 0
	v_mov_b32_e32 v46, 0
	v_mov_b32_e32 v47, 0
	v_mov_b32_e32 v50, 0
	v_mov_b32_e32 v51, 0
	v_mov_b32_e32 v54, 0
	v_mov_b32_e32 v55, 0
	v_mov_b32_e32 v58, 0
	v_mov_b32_e32 v59, 0
	v_mov_b32_e32 v62, 0
	v_mov_b32_e32 v63, 0
	v_mov_b32_e32 v68, 0
	v_mov_b32_e32 v69, 0
	v_mov_b32_e32 v72, 0
	v_mov_b32_e32 v73, 0
	v_mov_b32_e32 v76, 0
	v_mov_b32_e32 v77, 0
	ds_read_b128 v[130:133], v105
	ds_read_b128 v[134:137], v105 offset:1024
	ds_read_b128 v[138:141], v105 offset:2048
	ds_read_b128 v[142:145], v105 offset:3072
	ds_read_b128 v[146:149], v105 offset:4096
	ds_read_b128 v[150:153], v105 offset:5120
	ds_read_b128 v[154:157], v105 offset:6144
	ds_read_b128 v[158:161], v105 offset:7168
	ds_read_b128 v[162:165], v105 offset:8192
	ds_read_b128 v[166:169], v105 offset:9216
	ds_read_b128 v[170:173], v105 offset:10240
	ds_read_b128 v[174:177], v105 offset:11264
	ds_read_b128 v[178:181], v105 offset:12288
	ds_read_b128 v[182:185], v105 offset:13312
	ds_read_b128 v[186:189], v105 offset:14336
	ds_read_b128 v[190:193], v105 offset:15360
	ds_read_b128 v[194:197], v105 offset:16384
	ds_read_b128 v[198:201], v105 offset:17408
	ds_read_b128 v[204:207], v105 offset:18432
	ds_read_b128 v[208:211], v105 offset:19456
	ds_read_b128 v[212:215], v105 offset:20480
	ds_read_b128 v[216:219], v105 offset:21504
	ds_read_b128 v[220:223], v105 offset:22528
	ds_read_b128 v[224:227], v105 offset:23552
	ds_read_b128 v[228:231], v105 offset:24576
	ds_read_b128 v[232:235], v105 offset:25600
	ds_read_b128 v[236:239], v105 offset:26624
	ds_read_b128 v[240:243], v105 offset:27648
	ds_read_b128 v[244:247], v105 offset:28672
	ds_read_b128 v[248:251], v105 offset:29696
	ds_read_b128 v[114:117], v105 offset:30720
	ds_read_b128 v[118:121], v105 offset:31744
	s_waitcnt lgkmcnt(0)
.LBB0_527:
	s_waitcnt vmcnt(0)
	v_mov_b64_e32 v[18:19], v[2:3]
	v_mov_b64_e32 v[26:27], v[6:7]
	v_mov_b64_e32 v[16:17], v[0:1]
	v_add_u32_e32 v1, s0, v80
	v_mov_b64_e32 v[24:25], v[4:5]
	v_add_u32_e32 v0, 0x80, v1
	v_add_u32_e32 v2, 0x82, v1
	v_add_u32_e32 v4, 0x84, v1
	v_add_u32_e32 v6, 0x86, v1
	v_ashrrev_i32_e32 v1, 31, v0
	v_ashrrev_i32_e32 v3, 31, v2
	v_ashrrev_i32_e32 v5, 31, v4
	v_mov_b64_e32 v[22:23], v[10:11]
	v_ashrrev_i32_e32 v7, 31, v6
	v_lshlrev_b64 v[0:1], 10, v[0:1]
	v_lshlrev_b64 v[2:3], 10, v[2:3]
	v_lshlrev_b64 v[4:5], 10, v[4:5]
	v_mov_b64_e32 v[30:31], v[14:15]
	v_mov_b64_e32 v[20:21], v[8:9]
	v_lshlrev_b64 v[6:7], 10, v[6:7]
	v_lshl_add_u64 v[0:1], v[64:65], 0, v[0:1]
	v_lshl_add_u64 v[2:3], v[64:65], 0, v[2:3]
	v_lshl_add_u64 v[8:9], v[64:65], 0, v[4:5]
	v_mov_b64_e32 v[28:29], v[12:13]
	v_lshl_add_u64 v[32:33], v[64:65], 0, v[6:7]
	global_load_dwordx4 v[12:15], v[0:1], off
	global_load_dwordx4 v[4:7], v[2:3], off
	s_nop 0
	global_load_dwordx4 v[8:11], v[8:9], off
	s_nop 0
	global_load_dwordx4 v[0:3], v[32:33], off
	v_mov_b32_dpp v79, v72 row_ror:1 row_mask:0xf bank_mask:0xf bound_ctrl:1
	v_mov_b32_dpp v78, v70 row_ror:1 row_mask:0xf bank_mask:0xf bound_ctrl:1
	v_mov_b32_dpp v73, v73 row_ror:1 row_mask:0xf bank_mask:0xf bound_ctrl:1
	v_mov_b32_dpp v72, v71 row_ror:1 row_mask:0xf bank_mask:0xf bound_ctrl:1
	v_mfma_f32_16x16x32_bf16 v[32:35], v[130:133], v[28:31], 0
	v_mfma_f32_16x16x32_bf16 v[32:35], v[134:137], v[24:27], v[32:35]
	v_mfma_f32_16x16x32_bf16 v[82:85], v[194:197], v[28:31], 0
	v_mfma_f32_16x16x32_bf16 v[82:85], v[198:201], v[24:27], v[82:85]
	v_mfma_f32_16x16x32_bf16 v[32:35], v[138:141], v[20:23], v[32:35]
	v_mfma_f32_16x16x32_bf16 v[82:85], v[204:207], v[20:23], v[82:85]
	v_mfma_f32_16x16x32_bf16 v[86:89], v[142:145], v[16:19], v[32:35]
	s_nop 2
	v_mfma_f32_16x16x32_bf16 v[82:85], v[208:211], v[16:19], v[82:85]
	ds_read_b128 v[90:93], v109
	s_nop 0
	ds_read_b128 v[32:35], v109 offset:16
	s_waitcnt lgkmcnt(1)
	v_pk_mul_f32 v[94:95], v[90:91], v[78:79] op_sel:[0,1] op_sel_hi:[1,0]
	s_nop 0
	v_sub_f32_e32 v70, v94, v95
	v_pk_mul_f32 v[78:79], v[90:91], v[78:79]
	v_add_f32_e32 v81, v86, v70
	v_add_f32_e32 v70, v79, v78
	v_add_f32_e32 v78, v82, v70
	v_pk_mul_f32 v[70:71], v[92:93], v[72:73] op_sel:[0,1] op_sel_hi:[1,0]
	v_mov_b32_e32 v96, v91
	v_sub_f32_e32 v70, v70, v71
	v_add_f32_e32 v79, v70, v87
	v_pk_mul_f32 v[70:71], v[92:93], v[72:73]
	v_mov_b32_e32 v97, v93
	v_add_f32_e32 v70, v71, v70
	v_add_f32_e32 v94, v70, v83
	v_mov_b32_dpp v71, v76 row_ror:1 row_mask:0xf bank_mask:0xf bound_ctrl:1
	v_mov_b32_dpp v70, v74 row_ror:1 row_mask:0xf bank_mask:0xf bound_ctrl:1
	s_waitcnt lgkmcnt(0)
; #define SSM_SCAN_STEP(D, SQ) { _Pragma("unroll") for (int r = 0; r < 4; ++r) { \
;                     const float sr = dppf<DPP_SHR(D)>(Er[r]), si = dppf<DPP_SHR(D)>(Ei[r]); \
;                     Er[r] += mr[r] * sr - mi[r] * si; Ei[r] += mr[r] * si + mi[r] * sr; \
;                     if (SQ) { const float nr = mr[r] * mr[r] - mi[r] * mi[r], ni = 2.f * mr[r] * mi[r]; mr[r] = nr; mi[r] = ni; } } }
; template <bool PASS2>
; __device__ __forceinline__ void ssm_phase(const Params& p, const Frame& F0) {
;     ...
;                 for (int r = 0; r < 4; ++r) { hr[r] = dppf<DPP_ROR(1)>(xs[i][r]); hi[r] = dppf<DPP_ROR(1)>(xs[i + 4][r]);
;                     if (j == 0) { Er[r] += mr[r] * hr[r] - mi[r] * hi[r]; Ei[r] += mr[r] * hi[r] + mi[r] * hr[r]; } }
;     ...
;                 SSM_SCAN_STEP(1, 1) SSM_SCAN_STEP(2, 1) SSM_SCAN_STEP(4, 1) SSM_SCAN_STEP(8, 0)
	v_pk_mul_f32 v[72:73], v[32:33], v[70:71] op_sel:[0,1] op_sel_hi:[1,0]
	v_pk_mul_f32 v[70:71], v[32:33], v[70:71]
	v_sub_f32_e32 v72, v72, v73
	v_add_f32_e32 v70, v71, v70
	v_add_f32_e32 v76, v70, v84
	v_mov_b32_dpp v71, v77 row_ror:1 row_mask:0xf bank_mask:0xf bound_ctrl:1
	v_mov_b32_dpp v70, v75 row_ror:1 row_mask:0xf bank_mask:0xf bound_ctrl:1
	v_add_f32_e32 v74, v72, v88
	v_pk_mul_f32 v[72:73], v[34:35], v[70:71] op_sel:[0,1] op_sel_hi:[1,0]
	v_pk_mul_f32 v[70:71], v[34:35], v[70:71]
	v_sub_f32_e32 v72, v72, v73
	v_add_f32_e32 v70, v71, v70
	v_add_f32_e32 v70, v70, v85
	v_add_f32_e32 v72, v72, v89
	v_cndmask_b32_e64 v85, v85, v70, s[6:7]
	v_cndmask_b32_e64 v71, v83, v94, s[6:7]
	v_cndmask_b32_e64 v70, v82, v78, s[6:7]
	v_cndmask_b32_e64 v75, v89, v72, s[6:7]
	v_cndmask_b32_e64 v74, v88, v74, s[6:7]
	v_cndmask_b32_e64 v73, v87, v79, s[6:7]
	v_cndmask_b32_e64 v72, v86, v81, s[6:7]
	v_mov_b32_dpp v86, v70 row_shr:1 row_mask:0xf bank_mask:0xf bound_ctrl:1
	v_mov_b32_dpp v87, v71 row_shr:1 row_mask:0xf bank_mask:0xf bound_ctrl:1
	v_mov_b32_e32 v88, v90
	v_mov_b32_e32 v89, v92
	v_mov_b32_dpp v82, v72 row_shr:1 row_mask:0xf bank_mask:0xf bound_ctrl:1
	v_mov_b32_dpp v83, v73 row_shr:1 row_mask:0xf bank_mask:0xf bound_ctrl:1
	v_pk_mul_f32 v[94:95], v[88:89], v[86:87]
	v_pk_mul_f32 v[92:93], v[92:93], v[92:93]
	v_pk_fma_f32 v[94:95], v[96:97], v[82:83], v[94:95]
	v_pk_mul_f32 v[90:91], v[90:91], v[90:91]
	v_pk_add_f32 v[70:71], v[94:95], v[70:71]
	v_mov_b32_e32 v94, v90
	v_mov_b32_e32 v95, v92
	v_mov_b32_e32 v92, v91
	v_pk_mul_f32 v[86:87], v[96:97], v[86:87]
	v_pk_add_f32 v[90:91], v[94:95], v[92:93] neg_lo:[0,1] neg_hi:[0,1]
	v_pk_add_f32 v[92:93], v[88:89], v[88:89]
	v_pk_fma_f32 v[82:83], v[88:89], v[82:83], v[86:87] neg_lo:[0,0,1] neg_hi:[0,0,1]
	v_pk_mul_f32 v[92:93], v[96:97], v[92:93]
	v_mov_b32_dpp v94, v70 row_shr:2 row_mask:0xf bank_mask:0xf bound_ctrl:1
	v_mov_b32_dpp v95, v71 row_shr:2 row_mask:0xf bank_mask:0xf bound_ctrl:1
	v_pk_add_f32 v[72:73], v[82:83], v[72:73]
	v_pk_mul_f32 v[98:99], v[90:91], v[94:95]
	v_pk_mul_f32 v[86:87], v[92:93], v[94:95]
	v_mov_b32_dpp v82, v72 row_shr:2 row_mask:0xf bank_mask:0xf bound_ctrl:1
	v_mov_b32_dpp v83, v73 row_shr:2 row_mask:0xf bank_mask:0xf bound_ctrl:1
	v_pk_fma_f32 v[86:87], v[90:91], v[82:83], v[86:87] neg_lo:[0,0,1] neg_hi:[0,0,1]
	v_pk_fma_f32 v[82:83], v[92:93], v[82:83], v[98:99]
	v_pk_mul_f32 v[100:101], v[92:93], v[92:93]
	v_pk_add_f32 v[102:103], v[90:91], v[90:91]
	v_pk_add_f32 v[70:71], v[70:71], v[82:83]
	v_pk_fma_f32 v[100:101], v[90:91], v[90:91], v[100:101] neg_lo:[0,0,1] neg_hi:[0,0,1]
	v_pk_mul_f32 v[102:103], v[92:93], v[102:103]
	v_pk_add_f32 v[72:73], v[86:87], v[72:73]
	v_mov_b32_dpp v86, v70 row_shr:4 row_mask:0xf bank_mask:0xf bound_ctrl:1
	v_mov_b32_dpp v87, v71 row_shr:4 row_mask:0xf bank_mask:0xf bound_ctrl:1
	v_mov_b32_dpp v82, v72 row_shr:4 row_mask:0xf bank_mask:0xf bound_ctrl:1
	v_mov_b32_dpp v83, v73 row_shr:4 row_mask:0xf bank_mask:0xf bound_ctrl:1
	v_pk_mul_f32 v[88:89], v[102:103], v[86:87]
	v_pk_mul_f32 v[86:87], v[100:101], v[86:87]
	v_pk_fma_f32 v[88:89], v[100:101], v[82:83], v[88:89] neg_lo:[0,0,1] neg_hi:[0,0,1]
	v_pk_fma_f32 v[82:83], v[102:103], v[82:83], v[86:87]
	v_pk_mul_f32 v[110:111], v[102:103], v[102:103]
	v_pk_add_f32 v[112:113], v[100:101], v[100:101]
	v_pk_add_f32 v[70:71], v[70:71], v[82:83]
	v_pk_fma_f32 v[110:111], v[100:101], v[100:101], v[110:111] neg_lo:[0,0,1] neg_hi:[0,0,1]
	v_pk_mul_f32 v[112:113], v[102:103], v[112:113]
	v_pk_add_f32 v[72:73], v[72:73], v[88:89]
	v_mov_b32_dpp v86, v70 row_shr:8 row_mask:0xf bank_mask:0xf bound_ctrl:1
	v_mov_b32_dpp v87, v71 row_shr:8 row_mask:0xf bank_mask:0xf bound_ctrl:1
	v_mov_b32_dpp v82, v72 row_shr:8 row_mask:0xf bank_mask:0xf bound_ctrl:1
	v_mov_b32_dpp v83, v73 row_shr:8 row_mask:0xf bank_mask:0xf bound_ctrl:1
	v_pk_mul_f32 v[88:89], v[112:113], v[86:87]
	v_pk_mul_f32 v[86:87], v[110:111], v[86:87]
	v_cndmask_b32_e64 v84, v84, v76, s[6:7]
	v_pk_fma_f32 v[88:89], v[110:111], v[82:83], v[88:89] neg_lo:[0,0,1] neg_hi:[0,0,1]
	v_pk_fma_f32 v[82:83], v[112:113], v[82:83], v[86:87]
	v_mov_b32_dpp v78, v84 row_shr:1 row_mask:0xf bank_mask:0xf bound_ctrl:1
	v_mov_b32_dpp v79, v85 row_shr:1 row_mask:0xf bank_mask:0xf bound_ctrl:1
	v_pk_add_f32 v[70:71], v[70:71], v[82:83]
	v_mov_b32_e32 v82, v32
	v_mov_b32_e32 v83, v34
	v_mov_b32_dpp v76, v74 row_shr:1 row_mask:0xf bank_mask:0xf bound_ctrl:1
	v_mov_b32_dpp v77, v75 row_shr:1 row_mask:0xf bank_mask:0xf bound_ctrl:1
	v_pk_add_f32 v[72:73], v[72:73], v[88:89]
	v_pk_mul_f32 v[86:87], v[82:83], v[78:79]
	v_mov_b32_e32 v88, v33
	v_mov_b32_e32 v89, v35
	v_pk_fma_f32 v[86:87], v[88:89], v[76:77], v[86:87]
	v_pk_mul_f32 v[34:35], v[34:35], v[34:35]
	v_pk_mul_f32 v[32:33], v[32:33], v[32:33]
	v_pk_mul_f32 v[78:79], v[88:89], v[78:79]
	v_pk_add_f32 v[84:85], v[86:87], v[84:85]
	v_mov_b32_e32 v86, v32
	v_mov_b32_e32 v87, v34
	v_mov_b32_e32 v34, v33
	v_pk_fma_f32 v[76:77], v[82:83], v[76:77], v[78:79] neg_lo:[0,0,1] neg_hi:[0,0,1]
	v_pk_add_f32 v[32:33], v[86:87], v[34:35] neg_lo:[0,1] neg_hi:[0,1]
	v_pk_add_f32 v[34:35], v[82:83], v[82:83]
	v_mov_b32_dpp v86, v84 row_shr:2 row_mask:0xf bank_mask:0xf bound_ctrl:1
	v_mov_b32_dpp v87, v85 row_shr:2 row_mask:0xf bank_mask:0xf bound_ctrl:1
	v_pk_add_f32 v[74:75], v[76:77], v[74:75]
	v_pk_mul_f32 v[34:35], v[88:89], v[34:35]
	v_pk_mul_f32 v[90:91], v[32:33], v[86:87]
	v_pk_add_f32 v[94:95], v[32:33], v[32:33]
	v_mov_b32_dpp v76, v74 row_shr:2 row_mask:0xf bank_mask:0xf bound_ctrl:1
	v_mov_b32_dpp v77, v75 row_shr:2 row_mask:0xf bank_mask:0xf bound_ctrl:1
	v_pk_mul_f32 v[92:93], v[34:35], v[34:35]
; #define SSM_SCAN_STEP(D, SQ) { _Pragma("unroll") for (int r = 0; r < 4; ++r) { \
;                     const float sr = dppf<DPP_SHR(D)>(Er[r]), si = dppf<DPP_SHR(D)>(Ei[r]); \
;                     Er[r] += mr[r] * sr - mi[r] * si; Ei[r] += mr[r] * si + mi[r] * sr; \
;                     if (SQ) { const float nr = mr[r] * mr[r] - mi[r] * mi[r], ni = 2.f * mr[r] * mi[r]; mr[r] = nr; mi[r] = ni; } } }
; template <bool PASS2>
; __device__ __forceinline__ void ssm_phase(const Params& p, const Frame& F0) {
;     ...
;             for (int i = 0; i < 4; ++i) {
;                 __builtin_amdgcn_sched_barrier(0);
;                 f32x4 Er = (f32x4){0.f, 0.f, 0.f, 0.f}, Ei = Er;
; #pragma unroll
;                 for (int ks = 0; ks < 4; ++ks) { Er = __builtin_amdgcn_mfma_f32_16x16x32_bf16(frag[(i * 4 + ks) * 64], uf[ks], Er, 0, 0, 0);
;                                                  Ei = __builtin_amdgcn_mfma_f32_16x16x32_bf16(frag[((i + 4) * 4 + ks) * 64], uf[ks], Ei, 0, 0, 0); }
;                 const f32x4 ma = m1t[8 * i], mb = m1t[8 * i + 1];
;                 float mr[4] = {ma[0], ma[2], mb[0], mb[2]}, mi[4] = {ma[1], ma[3], mb[1], mb[3]};
;                 float hr[4], hi[4];
; #pragma unroll
;                 for (int r = 0; r < 4; ++r) { hr[r] = dppf<DPP_ROR(1)>(xs[i][r]); hi[r] = dppf<DPP_ROR(1)>(xs[i + 4][r]);
;                     if (j == 0) { Er[r] += mr[r] * hr[r] - mi[r] * hi[r]; Ei[r] += mr[r] * hi[r] + mi[r] * hr[r]; } }
;     ...
;                 SSM_SCAN_STEP(1, 1) SSM_SCAN_STEP(2, 1) SSM_SCAN_STEP(4, 1) SSM_SCAN_STEP(8, 0)
	v_pk_mul_f32 v[94:95], v[34:35], v[94:95]
	v_pk_mul_f32 v[78:79], v[34:35], v[86:87]
	v_pk_fma_f32 v[34:35], v[34:35], v[76:77], v[90:91]
	v_pk_fma_f32 v[92:93], v[32:33], v[32:33], v[92:93] neg_lo:[0,0,1] neg_hi:[0,0,1]
	v_pk_fma_f32 v[32:33], v[32:33], v[76:77], v[78:79] neg_lo:[0,0,1] neg_hi:[0,0,1]
	v_pk_add_f32 v[34:35], v[84:85], v[34:35]
	v_pk_add_f32 v[32:33], v[74:75], v[32:33]
	v_pk_add_f32 v[98:99], v[92:93], v[92:93]
	v_mov_b32_dpp v76, v34 row_shr:4 row_mask:0xf bank_mask:0xf bound_ctrl:1
	v_mov_b32_dpp v77, v35 row_shr:4 row_mask:0xf bank_mask:0xf bound_ctrl:1
	v_mov_b32_dpp v74, v32 row_shr:4 row_mask:0xf bank_mask:0xf bound_ctrl:1
	v_mov_b32_dpp v75, v33 row_shr:4 row_mask:0xf bank_mask:0xf bound_ctrl:1
	v_pk_mul_f32 v[78:79], v[94:95], v[76:77]
	v_pk_mul_f32 v[76:77], v[92:93], v[76:77]
	v_pk_fma_f32 v[78:79], v[92:93], v[74:75], v[78:79] neg_lo:[0,0,1] neg_hi:[0,0,1]
	v_pk_fma_f32 v[74:75], v[94:95], v[74:75], v[76:77]
	v_pk_mul_f32 v[96:97], v[94:95], v[94:95]
	v_pk_add_f32 v[34:35], v[34:35], v[74:75]
	v_pk_mul_f32 v[98:99], v[94:95], v[98:99]
	v_pk_add_f32 v[32:33], v[32:33], v[78:79]
	v_mov_b32_dpp v78, v34 row_shr:8 row_mask:0xf bank_mask:0xf bound_ctrl:1
	v_mov_b32_dpp v79, v35 row_shr:8 row_mask:0xf bank_mask:0xf bound_ctrl:1
	v_pk_fma_f32 v[96:97], v[92:93], v[92:93], v[96:97] neg_lo:[0,0,1] neg_hi:[0,0,1]
	v_mov_b32_dpp v74, v32 row_shr:8 row_mask:0xf bank_mask:0xf bound_ctrl:1
	v_mov_b32_dpp v75, v33 row_shr:8 row_mask:0xf bank_mask:0xf bound_ctrl:1
	v_pk_mul_f32 v[76:77], v[98:99], v[78:79]
	s_nop 0
	v_pk_fma_f32 v[76:77], v[96:97], v[74:75], v[76:77] neg_lo:[0,0,1] neg_hi:[0,0,1]
	s_nop 0
	v_pk_add_f32 v[76:77], v[32:33], v[76:77]
	v_pk_mul_f32 v[32:33], v[96:97], v[78:79]
	s_nop 0
	v_pk_fma_f32 v[32:33], v[98:99], v[74:75], v[32:33]
	s_nop 0
	v_pk_add_f32 v[74:75], v[34:35], v[32:33]
	v_mov_b32_dpp v79, v62 row_ror:1 row_mask:0xf bank_mask:0xf bound_ctrl:1
	v_mov_b32_dpp v78, v60 row_ror:1 row_mask:0xf bank_mask:0xf bound_ctrl:1
	v_mov_b32_dpp v63, v63 row_ror:1 row_mask:0xf bank_mask:0xf bound_ctrl:1
	v_mov_b32_dpp v62, v61 row_ror:1 row_mask:0xf bank_mask:0xf bound_ctrl:1
	v_mfma_f32_16x16x32_bf16 v[32:35], v[146:149], v[28:31], 0
	v_mfma_f32_16x16x32_bf16 v[32:35], v[150:153], v[24:27], v[32:35]
	v_mfma_f32_16x16x32_bf16 v[82:85], v[212:215], v[28:31], 0
	v_mfma_f32_16x16x32_bf16 v[82:85], v[216:219], v[24:27], v[82:85]
	v_mfma_f32_16x16x32_bf16 v[32:35], v[154:157], v[20:23], v[32:35]
	v_mfma_f32_16x16x32_bf16 v[82:85], v[220:223], v[20:23], v[82:85]
	v_mfma_f32_16x16x32_bf16 v[86:89], v[158:161], v[16:19], v[32:35]
	s_nop 2
	v_mfma_f32_16x16x32_bf16 v[82:85], v[224:227], v[16:19], v[82:85]
	ds_read_b128 v[90:93], v109 offset:128
	s_nop 0
	ds_read_b128 v[32:35], v109 offset:144
	s_waitcnt lgkmcnt(1)
	v_pk_mul_f32 v[94:95], v[90:91], v[78:79] op_sel:[0,1] op_sel_hi:[1,0]
	s_nop 0
	v_sub_f32_e32 v60, v94, v95
	v_pk_mul_f32 v[78:79], v[90:91], v[78:79]
	v_add_f32_e32 v81, v86, v60
	v_add_f32_e32 v60, v79, v78
	v_add_f32_e32 v78, v82, v60
	v_pk_mul_f32 v[60:61], v[92:93], v[62:63] op_sel:[0,1] op_sel_hi:[1,0]
	v_mov_b32_e32 v96, v91
	v_sub_f32_e32 v60, v60, v61
	v_add_f32_e32 v79, v60, v87
	v_pk_mul_f32 v[60:61], v[92:93], v[62:63]
	v_mov_b32_e32 v97, v93
	v_add_f32_e32 v60, v61, v60
	v_add_f32_e32 v94, v60, v83
	v_mov_b32_dpp v61, v68 row_ror:1 row_mask:0xf bank_mask:0xf bound_ctrl:1
	v_mov_b32_dpp v60, v66 row_ror:1 row_mask:0xf bank_mask:0xf bound_ctrl:1
	s_waitcnt lgkmcnt(0)
	v_pk_mul_f32 v[62:63], v[32:33], v[60:61] op_sel:[0,1] op_sel_hi:[1,0]
	v_pk_mul_f32 v[60:61], v[32:33], v[60:61]
	v_sub_f32_e32 v62, v62, v63
	v_add_f32_e32 v60, v61, v60
	v_add_f32_e32 v68, v60, v84
	v_mov_b32_dpp v61, v69 row_ror:1 row_mask:0xf bank_mask:0xf bound_ctrl:1
	v_mov_b32_dpp v60, v67 row_ror:1 row_mask:0xf bank_mask:0xf bound_ctrl:1
	v_add_f32_e32 v66, v62, v88
	v_pk_mul_f32 v[62:63], v[34:35], v[60:61] op_sel:[0,1] op_sel_hi:[1,0]
	v_pk_mul_f32 v[60:61], v[34:35], v[60:61]
	v_sub_f32_e32 v62, v62, v63
	v_add_f32_e32 v60, v61, v60
	v_add_f32_e32 v60, v60, v85
	v_add_f32_e32 v62, v62, v89
	v_cndmask_b32_e64 v85, v85, v60, s[6:7]
	v_cndmask_b32_e64 v61, v83, v94, s[6:7]
	v_cndmask_b32_e64 v60, v82, v78, s[6:7]
	v_cndmask_b32_e64 v67, v89, v62, s[6:7]
	v_cndmask_b32_e64 v66, v88, v66, s[6:7]
	v_cndmask_b32_e64 v63, v87, v79, s[6:7]
	v_cndmask_b32_e64 v62, v86, v81, s[6:7]
	v_mov_b32_dpp v86, v60 row_shr:1 row_mask:0xf bank_mask:0xf bound_ctrl:1
	v_mov_b32_dpp v87, v61 row_shr:1 row_mask:0xf bank_mask:0xf bound_ctrl:1
	v_mov_b32_e32 v88, v90
	v_mov_b32_e32 v89, v92
	v_mov_b32_dpp v82, v62 row_shr:1 row_mask:0xf bank_mask:0xf bound_ctrl:1
	v_mov_b32_dpp v83, v63 row_shr:1 row_mask:0xf bank_mask:0xf bound_ctrl:1
	v_pk_mul_f32 v[94:95], v[88:89], v[86:87]
	v_pk_mul_f32 v[92:93], v[92:93], v[92:93]
	v_pk_fma_f32 v[94:95], v[96:97], v[82:83], v[94:95]
	v_pk_mul_f32 v[90:91], v[90:91], v[90:91]
	v_pk_add_f32 v[60:61], v[94:95], v[60:61]
	v_mov_b32_e32 v94, v90
	v_mov_b32_e32 v95, v92
	v_mov_b32_e32 v92, v91
	v_pk_mul_f32 v[86:87], v[96:97], v[86:87]
	v_pk_add_f32 v[90:91], v[94:95], v[92:93] neg_lo:[0,1] neg_hi:[0,1]
	v_pk_add_f32 v[92:93], v[88:89], v[88:89]
	v_pk_fma_f32 v[82:83], v[88:89], v[82:83], v[86:87] neg_lo:[0,0,1] neg_hi:[0,0,1]
	v_pk_mul_f32 v[92:93], v[96:97], v[92:93]
	v_mov_b32_dpp v94, v60 row_shr:2 row_mask:0xf bank_mask:0xf bound_ctrl:1
	v_mov_b32_dpp v95, v61 row_shr:2 row_mask:0xf bank_mask:0xf bound_ctrl:1
	v_pk_add_f32 v[62:63], v[82:83], v[62:63]
	v_pk_mul_f32 v[98:99], v[90:91], v[94:95]
	v_pk_mul_f32 v[86:87], v[92:93], v[94:95]
	v_mov_b32_dpp v82, v62 row_shr:2 row_mask:0xf bank_mask:0xf bound_ctrl:1
; #define SSM_SCAN_STEP(D, SQ) { _Pragma("unroll") for (int r = 0; r < 4; ++r) { \
;                     const float sr = dppf<DPP_SHR(D)>(Er[r]), si = dppf<DPP_SHR(D)>(Ei[r]); \
;                     Er[r] += mr[r] * sr - mi[r] * si; Ei[r] += mr[r] * si + mi[r] * sr; \
;                     if (SQ) { const float nr = mr[r] * mr[r] - mi[r] * mi[r], ni = 2.f * mr[r] * mi[r]; mr[r] = nr; mi[r] = ni; } } }
; template <bool PASS2>
; __device__ __forceinline__ void ssm_phase(const Params& p, const Frame& F0) {
;     ...
;             for (int i = 0; i < 4; ++i) {
;                 __builtin_amdgcn_sched_barrier(0);
;                 f32x4 Er = (f32x4){0.f, 0.f, 0.f, 0.f}, Ei = Er;
; #pragma unroll
;                 for (int ks = 0; ks < 4; ++ks) { Er = __builtin_amdgcn_mfma_f32_16x16x32_bf16(frag[(i * 4 + ks) * 64], uf[ks], Er, 0, 0, 0);
;                                                  Ei = __builtin_amdgcn_mfma_f32_16x16x32_bf16(frag[((i + 4) * 4 + ks) * 64], uf[ks], Ei, 0, 0, 0); }
;                 const f32x4 ma = m1t[8 * i], mb = m1t[8 * i + 1];
;                 float mr[4] = {ma[0], ma[2], mb[0], mb[2]}, mi[4] = {ma[1], ma[3], mb[1], mb[3]};
;                 float hr[4], hi[4];
; #pragma unroll
;                 for (int r = 0; r < 4; ++r) { hr[r] = dppf<DPP_ROR(1)>(xs[i][r]); hi[r] = dppf<DPP_ROR(1)>(xs[i + 4][r]);
;                     if (j == 0) { Er[r] += mr[r] * hr[r] - mi[r] * hi[r]; Ei[r] += mr[r] * hi[r] + mi[r] * hr[r]; } }
;     ...
;                 SSM_SCAN_STEP(1, 1) SSM_SCAN_STEP(2, 1) SSM_SCAN_STEP(4, 1) SSM_SCAN_STEP(8, 0)
	v_mov_b32_dpp v83, v63 row_shr:2 row_mask:0xf bank_mask:0xf bound_ctrl:1
	v_pk_fma_f32 v[86:87], v[90:91], v[82:83], v[86:87] neg_lo:[0,0,1] neg_hi:[0,0,1]
	v_pk_fma_f32 v[82:83], v[92:93], v[82:83], v[98:99]
	v_pk_mul_f32 v[100:101], v[92:93], v[92:93]
	v_pk_add_f32 v[102:103], v[90:91], v[90:91]
	v_pk_add_f32 v[60:61], v[60:61], v[82:83]
	v_pk_fma_f32 v[100:101], v[90:91], v[90:91], v[100:101] neg_lo:[0,0,1] neg_hi:[0,0,1]
	v_pk_mul_f32 v[102:103], v[92:93], v[102:103]
	v_pk_add_f32 v[62:63], v[86:87], v[62:63]
	v_mov_b32_dpp v86, v60 row_shr:4 row_mask:0xf bank_mask:0xf bound_ctrl:1
	v_mov_b32_dpp v87, v61 row_shr:4 row_mask:0xf bank_mask:0xf bound_ctrl:1
	v_mov_b32_dpp v82, v62 row_shr:4 row_mask:0xf bank_mask:0xf bound_ctrl:1
	v_mov_b32_dpp v83, v63 row_shr:4 row_mask:0xf bank_mask:0xf bound_ctrl:1
	v_pk_mul_f32 v[88:89], v[102:103], v[86:87]
	v_pk_mul_f32 v[86:87], v[100:101], v[86:87]
	v_pk_fma_f32 v[88:89], v[100:101], v[82:83], v[88:89] neg_lo:[0,0,1] neg_hi:[0,0,1]
	v_pk_fma_f32 v[82:83], v[102:103], v[82:83], v[86:87]
	v_pk_mul_f32 v[110:111], v[102:103], v[102:103]
	v_pk_add_f32 v[112:113], v[100:101], v[100:101]
	v_pk_add_f32 v[60:61], v[60:61], v[82:83]
	v_pk_fma_f32 v[110:111], v[100:101], v[100:101], v[110:111] neg_lo:[0,0,1] neg_hi:[0,0,1]
	v_pk_mul_f32 v[112:113], v[102:103], v[112:113]
	v_pk_add_f32 v[62:63], v[62:63], v[88:89]
	v_mov_b32_dpp v86, v60 row_shr:8 row_mask:0xf bank_mask:0xf bound_ctrl:1
	v_mov_b32_dpp v87, v61 row_shr:8 row_mask:0xf bank_mask:0xf bound_ctrl:1
	v_mov_b32_dpp v82, v62 row_shr:8 row_mask:0xf bank_mask:0xf bound_ctrl:1
	v_mov_b32_dpp v83, v63 row_shr:8 row_mask:0xf bank_mask:0xf bound_ctrl:1
	v_pk_mul_f32 v[88:89], v[112:113], v[86:87]
	v_pk_mul_f32 v[86:87], v[110:111], v[86:87]
	v_cndmask_b32_e64 v84, v84, v68, s[6:7]
	v_pk_fma_f32 v[88:89], v[110:111], v[82:83], v[88:89] neg_lo:[0,0,1] neg_hi:[0,0,1]
	v_pk_fma_f32 v[82:83], v[112:113], v[82:83], v[86:87]
	v_mov_b32_dpp v78, v84 row_shr:1 row_mask:0xf bank_mask:0xf bound_ctrl:1
	v_mov_b32_dpp v79, v85 row_shr:1 row_mask:0xf bank_mask:0xf bound_ctrl:1
	v_pk_add_f32 v[60:61], v[60:61], v[82:83]
	v_mov_b32_e32 v82, v32
	v_mov_b32_e32 v83, v34
	v_mov_b32_dpp v68, v66 row_shr:1 row_mask:0xf bank_mask:0xf bound_ctrl:1
	v_mov_b32_dpp v69, v67 row_shr:1 row_mask:0xf bank_mask:0xf bound_ctrl:1
	v_pk_add_f32 v[62:63], v[62:63], v[88:89]
	v_pk_mul_f32 v[86:87], v[82:83], v[78:79]
	v_mov_b32_e32 v88, v33
	v_mov_b32_e32 v89, v35
	v_pk_fma_f32 v[86:87], v[88:89], v[68:69], v[86:87]
	v_pk_mul_f32 v[34:35], v[34:35], v[34:35]
	v_pk_mul_f32 v[32:33], v[32:33], v[32:33]
	v_pk_mul_f32 v[78:79], v[88:89], v[78:79]
	v_pk_add_f32 v[84:85], v[86:87], v[84:85]
	v_mov_b32_e32 v86, v32
	v_mov_b32_e32 v87, v34
	v_mov_b32_e32 v34, v33
	v_pk_fma_f32 v[68:69], v[82:83], v[68:69], v[78:79] neg_lo:[0,0,1] neg_hi:[0,0,1]
	v_pk_add_f32 v[32:33], v[86:87], v[34:35] neg_lo:[0,1] neg_hi:[0,1]
	v_pk_add_f32 v[34:35], v[82:83], v[82:83]
	v_mov_b32_dpp v86, v84 row_shr:2 row_mask:0xf bank_mask:0xf bound_ctrl:1
	v_mov_b32_dpp v87, v85 row_shr:2 row_mask:0xf bank_mask:0xf bound_ctrl:1
	v_pk_add_f32 v[66:67], v[68:69], v[66:67]
	v_pk_mul_f32 v[34:35], v[88:89], v[34:35]
	v_pk_mul_f32 v[90:91], v[32:33], v[86:87]
	v_pk_add_f32 v[94:95], v[32:33], v[32:33]
	v_mov_b32_dpp v68, v66 row_shr:2 row_mask:0xf bank_mask:0xf bound_ctrl:1
	v_mov_b32_dpp v69, v67 row_shr:2 row_mask:0xf bank_mask:0xf bound_ctrl:1
	v_pk_mul_f32 v[92:93], v[34:35], v[34:35]
	v_pk_mul_f32 v[94:95], v[34:35], v[94:95]
	v_pk_mul_f32 v[78:79], v[34:35], v[86:87]
	v_pk_fma_f32 v[34:35], v[34:35], v[68:69], v[90:91]
	v_pk_fma_f32 v[92:93], v[32:33], v[32:33], v[92:93] neg_lo:[0,0,1] neg_hi:[0,0,1]
	v_pk_fma_f32 v[32:33], v[32:33], v[68:69], v[78:79] neg_lo:[0,0,1] neg_hi:[0,0,1]
	v_pk_add_f32 v[34:35], v[84:85], v[34:35]
	v_pk_add_f32 v[32:33], v[66:67], v[32:33]
	v_pk_add_f32 v[98:99], v[92:93], v[92:93]
	v_mov_b32_dpp v68, v34 row_shr:4 row_mask:0xf bank_mask:0xf bound_ctrl:1
	v_mov_b32_dpp v69, v35 row_shr:4 row_mask:0xf bank_mask:0xf bound_ctrl:1
	v_mov_b32_dpp v66, v32 row_shr:4 row_mask:0xf bank_mask:0xf bound_ctrl:1
	v_mov_b32_dpp v67, v33 row_shr:4 row_mask:0xf bank_mask:0xf bound_ctrl:1
	v_pk_mul_f32 v[78:79], v[94:95], v[68:69]
	v_pk_mul_f32 v[68:69], v[92:93], v[68:69]
	v_pk_fma_f32 v[78:79], v[92:93], v[66:67], v[78:79] neg_lo:[0,0,1] neg_hi:[0,0,1]
	v_pk_fma_f32 v[66:67], v[94:95], v[66:67], v[68:69]
	v_pk_mul_f32 v[96:97], v[94:95], v[94:95]
	v_pk_add_f32 v[34:35], v[34:35], v[66:67]
	v_pk_mul_f32 v[98:99], v[94:95], v[98:99]
	v_pk_add_f32 v[32:33], v[32:33], v[78:79]
	v_mov_b32_dpp v78, v34 row_shr:8 row_mask:0xf bank_mask:0xf bound_ctrl:1
	v_mov_b32_dpp v79, v35 row_shr:8 row_mask:0xf bank_mask:0xf bound_ctrl:1
	v_pk_fma_f32 v[96:97], v[92:93], v[92:93], v[96:97] neg_lo:[0,0,1] neg_hi:[0,0,1]
	v_mov_b32_dpp v66, v32 row_shr:8 row_mask:0xf bank_mask:0xf bound_ctrl:1
	v_mov_b32_dpp v67, v33 row_shr:8 row_mask:0xf bank_mask:0xf bound_ctrl:1
	v_pk_mul_f32 v[68:69], v[98:99], v[78:79]
	s_nop 0
	v_pk_fma_f32 v[68:69], v[96:97], v[66:67], v[68:69] neg_lo:[0,0,1] neg_hi:[0,0,1]
	s_nop 0
	v_pk_add_f32 v[68:69], v[32:33], v[68:69]
	v_pk_mul_f32 v[32:33], v[96:97], v[78:79]
	s_nop 0
	v_pk_fma_f32 v[32:33], v[98:99], v[66:67], v[32:33]
	s_nop 0
	v_pk_add_f32 v[66:67], v[34:35], v[32:33]
	v_mov_b32_dpp v79, v54 row_ror:1 row_mask:0xf bank_mask:0xf bound_ctrl:1
	v_mov_b32_dpp v78, v52 row_ror:1 row_mask:0xf bank_mask:0xf bound_ctrl:1
	v_mov_b32_dpp v55, v55 row_ror:1 row_mask:0xf bank_mask:0xf bound_ctrl:1
	v_mov_b32_dpp v54, v53 row_ror:1 row_mask:0xf bank_mask:0xf bound_ctrl:1
	v_mfma_f32_16x16x32_bf16 v[32:35], v[162:165], v[28:31], 0
	v_mfma_f32_16x16x32_bf16 v[32:35], v[166:169], v[24:27], v[32:35]
	v_mfma_f32_16x16x32_bf16 v[82:85], v[228:231], v[28:31], 0
	v_mfma_f32_16x16x32_bf16 v[82:85], v[232:235], v[24:27], v[82:85]
	v_mfma_f32_16x16x32_bf16 v[32:35], v[170:173], v[20:23], v[32:35]
	v_mfma_f32_16x16x32_bf16 v[82:85], v[236:239], v[20:23], v[82:85]
	v_mfma_f32_16x16x32_bf16 v[86:89], v[174:177], v[16:19], v[32:35]
	s_nop 2
	v_mfma_f32_16x16x32_bf16 v[82:85], v[240:243], v[16:19], v[82:85]
	ds_read_b128 v[90:93], v109 offset:256
	s_nop 0
	ds_read_b128 v[32:35], v109 offset:272
	s_waitcnt lgkmcnt(1)
; #define SSM_SCAN_STEP(D, SQ) { _Pragma("unroll") for (int r = 0; r < 4; ++r) { \
;                     const float sr = dppf<DPP_SHR(D)>(Er[r]), si = dppf<DPP_SHR(D)>(Ei[r]); \
;                     Er[r] += mr[r] * sr - mi[r] * si; Ei[r] += mr[r] * si + mi[r] * sr; \
;                     if (SQ) { const float nr = mr[r] * mr[r] - mi[r] * mi[r], ni = 2.f * mr[r] * mi[r]; mr[r] = nr; mi[r] = ni; } } }
; template <bool PASS2>
; __device__ __forceinline__ void ssm_phase(const Params& p, const Frame& F0) {
;     ...
;                 const f32x4 ma = m1t[8 * i], mb = m1t[8 * i + 1];
;                 float mr[4] = {ma[0], ma[2], mb[0], mb[2]}, mi[4] = {ma[1], ma[3], mb[1], mb[3]};
;                 float hr[4], hi[4];
; #pragma unroll
;                 for (int r = 0; r < 4; ++r) { hr[r] = dppf<DPP_ROR(1)>(xs[i][r]); hi[r] = dppf<DPP_ROR(1)>(xs[i + 4][r]);
;                     if (j == 0) { Er[r] += mr[r] * hr[r] - mi[r] * hi[r]; Ei[r] += mr[r] * hi[r] + mi[r] * hr[r]; } }
;     ...
;                 SSM_SCAN_STEP(1, 1) SSM_SCAN_STEP(2, 1) SSM_SCAN_STEP(4, 1) SSM_SCAN_STEP(8, 0)
	v_pk_mul_f32 v[94:95], v[90:91], v[78:79] op_sel:[0,1] op_sel_hi:[1,0]
	s_nop 0
	v_sub_f32_e32 v52, v94, v95
	v_pk_mul_f32 v[78:79], v[90:91], v[78:79]
	v_add_f32_e32 v81, v86, v52
	v_add_f32_e32 v52, v79, v78
	v_add_f32_e32 v78, v82, v52
	v_pk_mul_f32 v[52:53], v[92:93], v[54:55] op_sel:[0,1] op_sel_hi:[1,0]
	v_mov_b32_e32 v96, v91
	v_sub_f32_e32 v52, v52, v53
	v_add_f32_e32 v79, v52, v87
	v_pk_mul_f32 v[52:53], v[92:93], v[54:55]
	v_mov_b32_e32 v97, v93
	v_add_f32_e32 v52, v53, v52
	v_add_f32_e32 v94, v52, v83
	v_mov_b32_dpp v53, v58 row_ror:1 row_mask:0xf bank_mask:0xf bound_ctrl:1
	v_mov_b32_dpp v52, v56 row_ror:1 row_mask:0xf bank_mask:0xf bound_ctrl:1
	s_waitcnt lgkmcnt(0)
	v_pk_mul_f32 v[54:55], v[32:33], v[52:53] op_sel:[0,1] op_sel_hi:[1,0]
	v_pk_mul_f32 v[52:53], v[32:33], v[52:53]
	v_sub_f32_e32 v54, v54, v55
	v_add_f32_e32 v52, v53, v52
	v_add_f32_e32 v58, v52, v84
	v_mov_b32_dpp v53, v59 row_ror:1 row_mask:0xf bank_mask:0xf bound_ctrl:1
	v_mov_b32_dpp v52, v57 row_ror:1 row_mask:0xf bank_mask:0xf bound_ctrl:1
	v_add_f32_e32 v56, v54, v88
	v_pk_mul_f32 v[54:55], v[34:35], v[52:53] op_sel:[0,1] op_sel_hi:[1,0]
	v_pk_mul_f32 v[52:53], v[34:35], v[52:53]
	v_sub_f32_e32 v54, v54, v55
	v_add_f32_e32 v52, v53, v52
	v_add_f32_e32 v52, v52, v85
	v_add_f32_e32 v54, v54, v89
	v_cndmask_b32_e64 v85, v85, v52, s[6:7]
	v_cndmask_b32_e64 v53, v83, v94, s[6:7]
	v_cndmask_b32_e64 v52, v82, v78, s[6:7]
	v_cndmask_b32_e64 v57, v89, v54, s[6:7]
	v_cndmask_b32_e64 v56, v88, v56, s[6:7]
	v_cndmask_b32_e64 v55, v87, v79, s[6:7]
	v_cndmask_b32_e64 v54, v86, v81, s[6:7]
	v_mov_b32_dpp v86, v52 row_shr:1 row_mask:0xf bank_mask:0xf bound_ctrl:1
	v_mov_b32_dpp v87, v53 row_shr:1 row_mask:0xf bank_mask:0xf bound_ctrl:1
	v_mov_b32_e32 v88, v90
	v_mov_b32_e32 v89, v92
	v_mov_b32_dpp v82, v54 row_shr:1 row_mask:0xf bank_mask:0xf bound_ctrl:1
	v_mov_b32_dpp v83, v55 row_shr:1 row_mask:0xf bank_mask:0xf bound_ctrl:1
	v_pk_mul_f32 v[94:95], v[88:89], v[86:87]
	v_pk_mul_f32 v[92:93], v[92:93], v[92:93]
	v_pk_fma_f32 v[94:95], v[96:97], v[82:83], v[94:95]
	v_pk_mul_f32 v[90:91], v[90:91], v[90:91]
	v_pk_add_f32 v[52:53], v[94:95], v[52:53]
	v_mov_b32_e32 v94, v90
	v_mov_b32_e32 v95, v92
	v_mov_b32_e32 v92, v91
	v_pk_mul_f32 v[86:87], v[96:97], v[86:87]
	v_pk_add_f32 v[90:91], v[94:95], v[92:93] neg_lo:[0,1] neg_hi:[0,1]
	v_pk_add_f32 v[92:93], v[88:89], v[88:89]
	v_pk_fma_f32 v[82:83], v[88:89], v[82:83], v[86:87] neg_lo:[0,0,1] neg_hi:[0,0,1]
	v_pk_mul_f32 v[92:93], v[96:97], v[92:93]
	v_mov_b32_dpp v94, v52 row_shr:2 row_mask:0xf bank_mask:0xf bound_ctrl:1
	v_mov_b32_dpp v95, v53 row_shr:2 row_mask:0xf bank_mask:0xf bound_ctrl:1
	v_pk_add_f32 v[54:55], v[82:83], v[54:55]
	v_pk_mul_f32 v[98:99], v[90:91], v[94:95]
	v_pk_mul_f32 v[86:87], v[92:93], v[94:95]
	v_mov_b32_dpp v82, v54 row_shr:2 row_mask:0xf bank_mask:0xf bound_ctrl:1
	v_mov_b32_dpp v83, v55 row_shr:2 row_mask:0xf bank_mask:0xf bound_ctrl:1
	v_pk_fma_f32 v[86:87], v[90:91], v[82:83], v[86:87] neg_lo:[0,0,1] neg_hi:[0,0,1]
	v_pk_fma_f32 v[82:83], v[92:93], v[82:83], v[98:99]
	v_pk_mul_f32 v[100:101], v[92:93], v[92:93]
	v_pk_add_f32 v[102:103], v[90:91], v[90:91]
	v_pk_add_f32 v[52:53], v[52:53], v[82:83]
	v_pk_fma_f32 v[100:101], v[90:91], v[90:91], v[100:101] neg_lo:[0,0,1] neg_hi:[0,0,1]
	v_pk_mul_f32 v[102:103], v[92:93], v[102:103]
	v_pk_add_f32 v[54:55], v[86:87], v[54:55]
	v_mov_b32_dpp v86, v52 row_shr:4 row_mask:0xf bank_mask:0xf bound_ctrl:1
	v_mov_b32_dpp v87, v53 row_shr:4 row_mask:0xf bank_mask:0xf bound_ctrl:1
	v_mov_b32_dpp v82, v54 row_shr:4 row_mask:0xf bank_mask:0xf bound_ctrl:1
	v_mov_b32_dpp v83, v55 row_shr:4 row_mask:0xf bank_mask:0xf bound_ctrl:1
	v_pk_mul_f32 v[88:89], v[102:103], v[86:87]
	v_pk_mul_f32 v[86:87], v[100:101], v[86:87]
	v_pk_fma_f32 v[88:89], v[100:101], v[82:83], v[88:89] neg_lo:[0,0,1] neg_hi:[0,0,1]
	v_pk_fma_f32 v[82:83], v[102:103], v[82:83], v[86:87]
	v_pk_mul_f32 v[110:111], v[102:103], v[102:103]
	v_pk_add_f32 v[112:113], v[100:101], v[100:101]
	v_pk_add_f32 v[52:53], v[52:53], v[82:83]
	v_pk_fma_f32 v[110:111], v[100:101], v[100:101], v[110:111] neg_lo:[0,0,1] neg_hi:[0,0,1]
	v_pk_mul_f32 v[112:113], v[102:103], v[112:113]
	v_pk_add_f32 v[54:55], v[54:55], v[88:89]
	v_mov_b32_dpp v86, v52 row_shr:8 row_mask:0xf bank_mask:0xf bound_ctrl:1
	v_mov_b32_dpp v87, v53 row_shr:8 row_mask:0xf bank_mask:0xf bound_ctrl:1
	v_mov_b32_dpp v82, v54 row_shr:8 row_mask:0xf bank_mask:0xf bound_ctrl:1
	v_mov_b32_dpp v83, v55 row_shr:8 row_mask:0xf bank_mask:0xf bound_ctrl:1
	v_pk_mul_f32 v[88:89], v[112:113], v[86:87]
	v_pk_mul_f32 v[86:87], v[110:111], v[86:87]
	v_cndmask_b32_e64 v84, v84, v58, s[6:7]
	v_pk_fma_f32 v[88:89], v[110:111], v[82:83], v[88:89] neg_lo:[0,0,1] neg_hi:[0,0,1]
	v_pk_fma_f32 v[82:83], v[112:113], v[82:83], v[86:87]
	v_mov_b32_dpp v78, v84 row_shr:1 row_mask:0xf bank_mask:0xf bound_ctrl:1
	v_mov_b32_dpp v79, v85 row_shr:1 row_mask:0xf bank_mask:0xf bound_ctrl:1
	v_pk_add_f32 v[52:53], v[52:53], v[82:83]
	v_mov_b32_e32 v82, v32
	v_mov_b32_e32 v83, v34
	v_mov_b32_dpp v58, v56 row_shr:1 row_mask:0xf bank_mask:0xf bound_ctrl:1
	v_mov_b32_dpp v59, v57 row_shr:1 row_mask:0xf bank_mask:0xf bound_ctrl:1
	v_pk_add_f32 v[54:55], v[54:55], v[88:89]
	v_pk_mul_f32 v[86:87], v[82:83], v[78:79]
	v_mov_b32_e32 v88, v33
	v_mov_b32_e32 v89, v35
	v_pk_fma_f32 v[86:87], v[88:89], v[58:59], v[86:87]
	v_pk_mul_f32 v[34:35], v[34:35], v[34:35]
	v_pk_mul_f32 v[32:33], v[32:33], v[32:33]
	v_pk_mul_f32 v[78:79], v[88:89], v[78:79]
	v_pk_add_f32 v[84:85], v[86:87], v[84:85]
	v_mov_b32_e32 v86, v32
	v_mov_b32_e32 v87, v34
	v_mov_b32_e32 v34, v33
; #define SSM_SCAN_STEP(D, SQ) { _Pragma("unroll") for (int r = 0; r < 4; ++r) { \
;                     const float sr = dppf<DPP_SHR(D)>(Er[r]), si = dppf<DPP_SHR(D)>(Ei[r]); \
;                     Er[r] += mr[r] * sr - mi[r] * si; Ei[r] += mr[r] * si + mi[r] * sr; \
;                     if (SQ) { const float nr = mr[r] * mr[r] - mi[r] * mi[r], ni = 2.f * mr[r] * mi[r]; mr[r] = nr; mi[r] = ni; } } }
; template <bool PASS2>
; __device__ __forceinline__ void ssm_phase(const Params& p, const Frame& F0) {
;     ...
;             for (int i = 0; i < 4; ++i) {
;                 __builtin_amdgcn_sched_barrier(0);
;                 f32x4 Er = (f32x4){0.f, 0.f, 0.f, 0.f}, Ei = Er;
; #pragma unroll
;                 for (int ks = 0; ks < 4; ++ks) { Er = __builtin_amdgcn_mfma_f32_16x16x32_bf16(frag[(i * 4 + ks) * 64], uf[ks], Er, 0, 0, 0);
;                                                  Ei = __builtin_amdgcn_mfma_f32_16x16x32_bf16(frag[((i + 4) * 4 + ks) * 64], uf[ks], Ei, 0, 0, 0); }
;                 const f32x4 ma = m1t[8 * i], mb = m1t[8 * i + 1];
;                 float mr[4] = {ma[0], ma[2], mb[0], mb[2]}, mi[4] = {ma[1], ma[3], mb[1], mb[3]};
;                 float hr[4], hi[4];
; #pragma unroll
;                 for (int r = 0; r < 4; ++r) { hr[r] = dppf<DPP_ROR(1)>(xs[i][r]); hi[r] = dppf<DPP_ROR(1)>(xs[i + 4][r]);
;                     if (j == 0) { Er[r] += mr[r] * hr[r] - mi[r] * hi[r]; Ei[r] += mr[r] * hi[r] + mi[r] * hr[r]; } }
;     ...
;                 SSM_SCAN_STEP(1, 1) SSM_SCAN_STEP(2, 1) SSM_SCAN_STEP(4, 1) SSM_SCAN_STEP(8, 0)
	v_pk_fma_f32 v[58:59], v[82:83], v[58:59], v[78:79] neg_lo:[0,0,1] neg_hi:[0,0,1]
	v_pk_add_f32 v[32:33], v[86:87], v[34:35] neg_lo:[0,1] neg_hi:[0,1]
	v_pk_add_f32 v[34:35], v[82:83], v[82:83]
	v_mov_b32_dpp v86, v84 row_shr:2 row_mask:0xf bank_mask:0xf bound_ctrl:1
	v_mov_b32_dpp v87, v85 row_shr:2 row_mask:0xf bank_mask:0xf bound_ctrl:1
	v_pk_add_f32 v[56:57], v[58:59], v[56:57]
	v_pk_mul_f32 v[34:35], v[88:89], v[34:35]
	v_pk_mul_f32 v[90:91], v[32:33], v[86:87]
	v_pk_add_f32 v[94:95], v[32:33], v[32:33]
	v_mov_b32_dpp v58, v56 row_shr:2 row_mask:0xf bank_mask:0xf bound_ctrl:1
	v_mov_b32_dpp v59, v57 row_shr:2 row_mask:0xf bank_mask:0xf bound_ctrl:1
	v_pk_mul_f32 v[92:93], v[34:35], v[34:35]
	v_pk_mul_f32 v[94:95], v[34:35], v[94:95]
	v_pk_mul_f32 v[78:79], v[34:35], v[86:87]
	v_pk_fma_f32 v[34:35], v[34:35], v[58:59], v[90:91]
	v_pk_fma_f32 v[92:93], v[32:33], v[32:33], v[92:93] neg_lo:[0,0,1] neg_hi:[0,0,1]
	v_pk_fma_f32 v[32:33], v[32:33], v[58:59], v[78:79] neg_lo:[0,0,1] neg_hi:[0,0,1]
	v_pk_add_f32 v[34:35], v[84:85], v[34:35]
	v_pk_add_f32 v[32:33], v[56:57], v[32:33]
	v_pk_add_f32 v[98:99], v[92:93], v[92:93]
	v_mov_b32_dpp v58, v34 row_shr:4 row_mask:0xf bank_mask:0xf bound_ctrl:1
	v_mov_b32_dpp v59, v35 row_shr:4 row_mask:0xf bank_mask:0xf bound_ctrl:1
	v_mov_b32_dpp v56, v32 row_shr:4 row_mask:0xf bank_mask:0xf bound_ctrl:1
	v_mov_b32_dpp v57, v33 row_shr:4 row_mask:0xf bank_mask:0xf bound_ctrl:1
	v_pk_mul_f32 v[78:79], v[94:95], v[58:59]
	v_pk_mul_f32 v[58:59], v[92:93], v[58:59]
	v_pk_fma_f32 v[78:79], v[92:93], v[56:57], v[78:79] neg_lo:[0,0,1] neg_hi:[0,0,1]
	v_pk_fma_f32 v[56:57], v[94:95], v[56:57], v[58:59]
	v_pk_mul_f32 v[96:97], v[94:95], v[94:95]
	v_pk_add_f32 v[34:35], v[34:35], v[56:57]
	v_pk_mul_f32 v[98:99], v[94:95], v[98:99]
	v_pk_add_f32 v[32:33], v[32:33], v[78:79]
	v_mov_b32_dpp v78, v34 row_shr:8 row_mask:0xf bank_mask:0xf bound_ctrl:1
	v_mov_b32_dpp v79, v35 row_shr:8 row_mask:0xf bank_mask:0xf bound_ctrl:1
	v_pk_fma_f32 v[96:97], v[92:93], v[92:93], v[96:97] neg_lo:[0,0,1] neg_hi:[0,0,1]
	v_mov_b32_dpp v56, v32 row_shr:8 row_mask:0xf bank_mask:0xf bound_ctrl:1
	v_mov_b32_dpp v57, v33 row_shr:8 row_mask:0xf bank_mask:0xf bound_ctrl:1
	v_pk_mul_f32 v[58:59], v[98:99], v[78:79]
	s_nop 0
	v_pk_fma_f32 v[58:59], v[96:97], v[56:57], v[58:59] neg_lo:[0,0,1] neg_hi:[0,0,1]
	s_nop 0
	v_pk_add_f32 v[58:59], v[32:33], v[58:59]
	v_pk_mul_f32 v[32:33], v[96:97], v[78:79]
	s_nop 0
	v_pk_fma_f32 v[32:33], v[98:99], v[56:57], v[32:33]
	s_nop 0
	v_pk_add_f32 v[56:57], v[34:35], v[32:33]
	v_mfma_f32_16x16x32_bf16 v[32:35], v[178:181], v[28:31], 0
	v_mfma_f32_16x16x32_bf16 v[28:31], v[244:247], v[28:31], 0
	v_mfma_f32_16x16x32_bf16 v[32:35], v[182:185], v[24:27], v[32:35]
	v_mfma_f32_16x16x32_bf16 v[24:27], v[248:251], v[24:27], v[28:31]
	s_nop 2
	v_mfma_f32_16x16x32_bf16 v[28:31], v[186:189], v[20:23], v[32:35]
	s_nop 2
	v_mfma_f32_16x16x32_bf16 v[20:23], v[114:117], v[20:23], v[24:27]
	s_nop 2
	v_mov_b32_dpp v33, v46 row_ror:1 row_mask:0xf bank_mask:0xf bound_ctrl:1
	v_mov_b32_dpp v32, v44 row_ror:1 row_mask:0xf bank_mask:0xf bound_ctrl:1
	v_mfma_f32_16x16x32_bf16 v[24:27], v[190:193], v[16:19], v[28:31]
	s_nop 2
	v_mfma_f32_16x16x32_bf16 v[20:23], v[118:121], v[16:19], v[20:23]
	ds_read_b128 v[28:31], v109 offset:384
	ds_read_b128 v[16:19], v109 offset:400
	s_waitcnt lgkmcnt(1)
	v_pk_mul_f32 v[34:35], v[28:29], v[32:33] op_sel:[0,1] op_sel_hi:[1,0]
	v_pk_mul_f32 v[32:33], v[28:29], v[32:33]
	v_sub_f32_e32 v34, v34, v35
	v_add_f32_e32 v32, v33, v32
	s_nop 0
	v_add_f32_e32 v46, v20, v32
	v_mov_b32_dpp v33, v47 row_ror:1 row_mask:0xf bank_mask:0xf bound_ctrl:1
	v_mov_b32_dpp v32, v45 row_ror:1 row_mask:0xf bank_mask:0xf bound_ctrl:1
	v_add_f32_e32 v44, v24, v34
	v_pk_mul_f32 v[34:35], v[30:31], v[32:33] op_sel:[0,1] op_sel_hi:[1,0]
	v_pk_mul_f32 v[32:33], v[30:31], v[32:33]
	v_sub_f32_e32 v34, v34, v35
	v_add_f32_e32 v32, v33, v32
	v_add_f32_e32 v47, v32, v21
	v_mov_b32_dpp v33, v50 row_ror:1 row_mask:0xf bank_mask:0xf bound_ctrl:1
	v_mov_b32_dpp v32, v48 row_ror:1 row_mask:0xf bank_mask:0xf bound_ctrl:1
	v_add_f32_e32 v45, v34, v25
	s_waitcnt lgkmcnt(0)
	v_pk_mul_f32 v[34:35], v[16:17], v[32:33] op_sel:[0,1] op_sel_hi:[1,0]
	v_pk_mul_f32 v[32:33], v[16:17], v[32:33]
	v_sub_f32_e32 v34, v34, v35
	v_add_f32_e32 v32, v33, v32
	v_add_f32_e32 v50, v32, v22
	v_mov_b32_dpp v33, v51 row_ror:1 row_mask:0xf bank_mask:0xf bound_ctrl:1
	v_mov_b32_dpp v32, v49 row_ror:1 row_mask:0xf bank_mask:0xf bound_ctrl:1
	v_add_f32_e32 v48, v34, v26
	v_pk_mul_f32 v[34:35], v[18:19], v[32:33] op_sel:[0,1] op_sel_hi:[1,0]
	v_pk_mul_f32 v[32:33], v[18:19], v[32:33]
	v_sub_f32_e32 v34, v34, v35
	v_add_f32_e32 v49, v34, v27
	v_add_f32_e32 v32, v33, v32
	v_cndmask_b32_e64 v35, v21, v47, s[6:7]
	v_cndmask_b32_e64 v34, v20, v46, s[6:7]
	v_add_f32_e32 v32, v32, v23
	v_cndmask_b32_e64 v21, v27, v49, s[6:7]
	v_cndmask_b32_e64 v20, v26, v48, s[6:7]
	v_cndmask_b32_e64 v27, v25, v45, s[6:7]
	v_cndmask_b32_e64 v26, v24, v44, s[6:7]
	v_mov_b32_dpp v46, v34 row_shr:1 row_mask:0xf bank_mask:0xf bound_ctrl:1
	v_mov_b32_dpp v47, v35 row_shr:1 row_mask:0xf bank_mask:0xf bound_ctrl:1
	v_mov_b32_e32 v48, v28
	v_mov_b32_e32 v49, v30
	v_cndmask_b32_e64 v33, v23, v32, s[6:7]
	v_cndmask_b32_e64 v32, v22, v50, s[6:7]
	v_mov_b32_dpp v44, v26 row_shr:1 row_mask:0xf bank_mask:0xf bound_ctrl:1
	v_mov_b32_dpp v45, v27 row_shr:1 row_mask:0xf bank_mask:0xf bound_ctrl:1
	v_pk_mul_f32 v[50:51], v[48:49], v[46:47]
	v_mov_b32_e32 v78, v29
	v_mov_b32_e32 v79, v31
	v_pk_fma_f32 v[50:51], v[78:79], v[44:45], v[50:51]
	v_pk_mul_f32 v[30:31], v[30:31], v[30:31]
; __device__ __forceinline__ unsigned cvt_pk_bf16(float lo, float hi) { unsigned r; asm("v_cvt_pk_bf16_f32 %0, %1, %2" : "=v"(r) : "v"(lo), "v"(hi)); return r; }
; #define SSM_SCAN_STEP(D, SQ) { _Pragma("unroll") for (int r = 0; r < 4; ++r) { \
;                     const float sr = dppf<DPP_SHR(D)>(Er[r]), si = dppf<DPP_SHR(D)>(Ei[r]); \
;                     Er[r] += mr[r] * sr - mi[r] * si; Ei[r] += mr[r] * si + mi[r] * sr; \
;                     if (SQ) { const float nr = mr[r] * mr[r] - mi[r] * mi[r], ni = 2.f * mr[r] * mi[r]; mr[r] = nr; mi[r] = ni; } } }
; template <bool PASS2>
; __device__ __forceinline__ void ssm_phase(const Params& p, const Frame& F0) {
;     ...
;                 SSM_SCAN_STEP(1, 1) SSM_SCAN_STEP(2, 1) SSM_SCAN_STEP(4, 1) SSM_SCAN_STEP(8, 0)
;     ...
;                 if constexpr (PASS2) {
;                     float vr[4], vi[4];
; #pragma unroll
;                     for (int r = 0; r < 4; ++r) { const float pr_ = dppf<DPP_ROR(1)>(Er[r]), pi_ = dppf<DPP_ROR(1)>(Ei[r]); vr[r] = (j == 0) ? hr[r] : pr_; vi[r] = (j == 0) ? hi[r] : pi_; }
;                     hw[i >> 1][2 * (i & 1)] = cvt_pk_bf16(vr[0], vr[1]); hw[i >> 1][2 * (i & 1) + 1] = cvt_pk_bf16(vr[2], vr[3]);
;                     hw[2 + (i >> 1)][2 * (i & 1)] = cvt_pk_bf16(vi[0], vi[1]); hw[2 + (i >> 1)][2 * (i & 1) + 1] = cvt_pk_bf16(vi[2], vi[3]);
;                 }
;                 xs[i] = Er; xs[i + 4] = Ei;
	v_pk_mul_f32 v[28:29], v[28:29], v[28:29]
	v_pk_add_f32 v[34:35], v[50:51], v[34:35]
	v_mov_b32_e32 v50, v28
	v_mov_b32_e32 v51, v30
	v_mov_b32_e32 v30, v29
	v_pk_mul_f32 v[46:47], v[78:79], v[46:47]
	v_pk_add_f32 v[28:29], v[50:51], v[30:31] neg_lo:[0,1] neg_hi:[0,1]
	v_pk_add_f32 v[30:31], v[48:49], v[48:49]
	v_pk_fma_f32 v[44:45], v[48:49], v[44:45], v[46:47] neg_lo:[0,0,1] neg_hi:[0,0,1]
	v_pk_mul_f32 v[30:31], v[78:79], v[30:31]
	v_mov_b32_dpp v50, v34 row_shr:2 row_mask:0xf bank_mask:0xf bound_ctrl:1
	v_mov_b32_dpp v51, v35 row_shr:2 row_mask:0xf bank_mask:0xf bound_ctrl:1
	v_pk_add_f32 v[26:27], v[44:45], v[26:27]
	v_pk_mul_f32 v[84:85], v[30:31], v[30:31]
	v_pk_mul_f32 v[46:47], v[30:31], v[50:51]
	v_mov_b32_dpp v44, v26 row_shr:2 row_mask:0xf bank_mask:0xf bound_ctrl:1
	v_mov_b32_dpp v45, v27 row_shr:2 row_mask:0xf bank_mask:0xf bound_ctrl:1
	v_pk_mul_f32 v[82:83], v[28:29], v[50:51]
	v_pk_fma_f32 v[84:85], v[28:29], v[28:29], v[84:85] neg_lo:[0,0,1] neg_hi:[0,0,1]
	v_pk_add_f32 v[86:87], v[28:29], v[28:29]
	v_pk_fma_f32 v[28:29], v[28:29], v[44:45], v[46:47] neg_lo:[0,0,1] neg_hi:[0,0,1]
	v_pk_mul_f32 v[86:87], v[30:31], v[86:87]
	v_pk_add_f32 v[26:27], v[28:29], v[26:27]
	v_pk_fma_f32 v[28:29], v[30:31], v[44:45], v[82:83]
	v_pk_add_f32 v[90:91], v[84:85], v[84:85]
	v_pk_add_f32 v[28:29], v[34:35], v[28:29]
	v_mov_b32_dpp v30, v26 row_shr:4 row_mask:0xf bank_mask:0xf bound_ctrl:1
	v_mov_b32_dpp v31, v27 row_shr:4 row_mask:0xf bank_mask:0xf bound_ctrl:1
	v_mov_b32_dpp v34, v28 row_shr:4 row_mask:0xf bank_mask:0xf bound_ctrl:1
	v_mov_b32_dpp v35, v29 row_shr:4 row_mask:0xf bank_mask:0xf bound_ctrl:1
	v_pk_mul_f32 v[44:45], v[86:87], v[34:35]
	v_pk_mul_f32 v[34:35], v[84:85], v[34:35]
	v_pk_fma_f32 v[44:45], v[84:85], v[30:31], v[44:45] neg_lo:[0,0,1] neg_hi:[0,0,1]
	v_pk_fma_f32 v[30:31], v[86:87], v[30:31], v[34:35]
	v_pk_mul_f32 v[88:89], v[86:87], v[86:87]
	v_pk_add_f32 v[28:29], v[28:29], v[30:31]
	v_pk_mul_f32 v[90:91], v[86:87], v[90:91]
	v_pk_add_f32 v[26:27], v[26:27], v[44:45]
	v_mov_b32_dpp v34, v28 row_shr:8 row_mask:0xf bank_mask:0xf bound_ctrl:1
	v_mov_b32_dpp v35, v29 row_shr:8 row_mask:0xf bank_mask:0xf bound_ctrl:1
	v_pk_fma_f32 v[88:89], v[84:85], v[84:85], v[88:89] neg_lo:[0,0,1] neg_hi:[0,0,1]
	v_mov_b32_dpp v30, v26 row_shr:8 row_mask:0xf bank_mask:0xf bound_ctrl:1
	v_mov_b32_dpp v31, v27 row_shr:8 row_mask:0xf bank_mask:0xf bound_ctrl:1
	v_pk_mul_f32 v[44:45], v[90:91], v[34:35]
	v_mov_b32_dpp v24, v32 row_shr:1 row_mask:0xf bank_mask:0xf bound_ctrl:1
	v_pk_fma_f32 v[44:45], v[88:89], v[30:31], v[44:45] neg_lo:[0,0,1] neg_hi:[0,0,1]
	v_mov_b32_dpp v25, v33 row_shr:1 row_mask:0xf bank_mask:0xf bound_ctrl:1
	v_pk_add_f32 v[46:47], v[26:27], v[44:45]
	v_pk_mul_f32 v[26:27], v[88:89], v[34:35]
	v_mov_b32_dpp v22, v20 row_shr:1 row_mask:0xf bank_mask:0xf bound_ctrl:1
	v_pk_fma_f32 v[26:27], v[90:91], v[30:31], v[26:27]
	v_mov_b32_dpp v23, v21 row_shr:1 row_mask:0xf bank_mask:0xf bound_ctrl:1
	v_pk_add_f32 v[44:45], v[28:29], v[26:27]
	v_mov_b32_e32 v26, v16
	v_mov_b32_e32 v27, v18
	v_pk_mul_f32 v[28:29], v[26:27], v[24:25]
	v_mov_b32_e32 v30, v17
	v_mov_b32_e32 v31, v19
	v_pk_fma_f32 v[28:29], v[30:31], v[22:23], v[28:29]
	v_pk_mul_f32 v[18:19], v[18:19], v[18:19]
	v_pk_mul_f32 v[16:17], v[16:17], v[16:17]
	v_pk_mul_f32 v[24:25], v[30:31], v[24:25]
	v_pk_add_f32 v[28:29], v[28:29], v[32:33]
	v_mov_b32_e32 v32, v16
	v_mov_b32_e32 v33, v18
	v_mov_b32_e32 v18, v17
	v_pk_fma_f32 v[22:23], v[26:27], v[22:23], v[24:25] neg_lo:[0,0,1] neg_hi:[0,0,1]
	v_pk_add_f32 v[16:17], v[32:33], v[18:19] neg_lo:[0,1] neg_hi:[0,1]
	v_pk_add_f32 v[18:19], v[26:27], v[26:27]
	v_mov_b32_dpp v32, v28 row_shr:2 row_mask:0xf bank_mask:0xf bound_ctrl:1
	v_mov_b32_dpp v33, v29 row_shr:2 row_mask:0xf bank_mask:0xf bound_ctrl:1
	v_pk_add_f32 v[20:21], v[22:23], v[20:21]
	v_pk_mul_f32 v[18:19], v[30:31], v[18:19]
	v_pk_mul_f32 v[34:35], v[16:17], v[32:33]
	v_pk_add_f32 v[50:51], v[16:17], v[16:17]
	v_mov_b32_dpp v22, v20 row_shr:2 row_mask:0xf bank_mask:0xf bound_ctrl:1
	v_mov_b32_dpp v23, v21 row_shr:2 row_mask:0xf bank_mask:0xf bound_ctrl:1
	v_pk_mul_f32 v[48:49], v[18:19], v[18:19]
	v_pk_mul_f32 v[50:51], v[18:19], v[50:51]
	v_pk_mul_f32 v[24:25], v[18:19], v[32:33]
	v_pk_fma_f32 v[18:19], v[18:19], v[22:23], v[34:35]
	v_pk_fma_f32 v[48:49], v[16:17], v[16:17], v[48:49] neg_lo:[0,0,1] neg_hi:[0,0,1]
	v_pk_fma_f32 v[16:17], v[16:17], v[22:23], v[24:25] neg_lo:[0,0,1] neg_hi:[0,0,1]
	v_pk_add_f32 v[18:19], v[28:29], v[18:19]
	v_pk_add_f32 v[16:17], v[20:21], v[16:17]
	v_pk_add_f32 v[82:83], v[48:49], v[48:49]
	v_mov_b32_dpp v22, v18 row_shr:4 row_mask:0xf bank_mask:0xf bound_ctrl:1
	v_mov_b32_dpp v23, v19 row_shr:4 row_mask:0xf bank_mask:0xf bound_ctrl:1
	v_mov_b32_dpp v20, v16 row_shr:4 row_mask:0xf bank_mask:0xf bound_ctrl:1
	v_mov_b32_dpp v21, v17 row_shr:4 row_mask:0xf bank_mask:0xf bound_ctrl:1
	v_pk_mul_f32 v[24:25], v[50:51], v[22:23]
	v_pk_mul_f32 v[22:23], v[48:49], v[22:23]
	v_pk_fma_f32 v[24:25], v[48:49], v[20:21], v[24:25] neg_lo:[0,0,1] neg_hi:[0,0,1]
	v_pk_fma_f32 v[20:21], v[50:51], v[20:21], v[22:23]
	v_pk_mul_f32 v[78:79], v[50:51], v[50:51]
	v_pk_add_f32 v[18:19], v[18:19], v[20:21]
	v_pk_mul_f32 v[82:83], v[50:51], v[82:83]
	v_pk_add_f32 v[16:17], v[16:17], v[24:25]
	v_mov_b32_dpp v22, v18 row_shr:8 row_mask:0xf bank_mask:0xf bound_ctrl:1
	v_mov_b32_dpp v23, v19 row_shr:8 row_mask:0xf bank_mask:0xf bound_ctrl:1
	v_pk_fma_f32 v[78:79], v[48:49], v[48:49], v[78:79] neg_lo:[0,0,1] neg_hi:[0,0,1]
	v_mov_b32_dpp v20, v16 row_shr:8 row_mask:0xf bank_mask:0xf bound_ctrl:1
	v_mov_b32_dpp v21, v17 row_shr:8 row_mask:0xf bank_mask:0xf bound_ctrl:1
	v_pk_mul_f32 v[24:25], v[82:83], v[22:23]
	s_nop 0
	v_pk_fma_f32 v[24:25], v[78:79], v[20:21], v[24:25] neg_lo:[0,0,1] neg_hi:[0,0,1]
	s_nop 0
	v_pk_add_f32 v[50:51], v[16:17], v[24:25]
	v_pk_mul_f32 v[16:17], v[78:79], v[22:23]
	s_nop 0
	v_pk_fma_f32 v[16:17], v[82:83], v[20:21], v[16:17]
	s_nop 0
	v_pk_add_f32 v[48:49], v[18:19], v[16:17]
	s_addk_i32 s0, 0x80
	s_cmpk_eq_i32 s0, 0x180
	s_cbranch_scc0 .LBB0_527
; #define SSM_SCAN_STEP(D, SQ) { _Pragma("unroll") for (int r = 0; r < 4; ++r) { \
;                     const float sr = dppf<DPP_SHR(D)>(Er[r]), si = dppf<DPP_SHR(D)>(Ei[r]); \
;                     Er[r] += mr[r] * sr - mi[r] * si; Ei[r] += mr[r] * si + mi[r] * sr; \
;                     if (SQ) { const float nr = mr[r] * mr[r] - mi[r] * mi[r], ni = 2.f * mr[r] * mi[r]; mr[r] = nr; mi[r] = ni; } } }
; template <bool PASS2>
; __device__ __forceinline__ void ssm_phase(const Params& p, const Frame& F0) {
;     ...
;             for (int i = 0; i < 4; ++i) {
;                 __builtin_amdgcn_sched_barrier(0);
;                 f32x4 Er = (f32x4){0.f, 0.f, 0.f, 0.f}, Ei = Er;
; #pragma unroll
;                 for (int ks = 0; ks < 4; ++ks) { Er = __builtin_amdgcn_mfma_f32_16x16x32_bf16(frag[(i * 4 + ks) * 64], uf[ks], Er, 0, 0, 0);
;                                                  Ei = __builtin_amdgcn_mfma_f32_16x16x32_bf16(frag[((i + 4) * 4 + ks) * 64], uf[ks], Ei, 0, 0, 0); }
;                 const f32x4 ma = m1t[8 * i], mb = m1t[8 * i + 1];
;                 float mr[4] = {ma[0], ma[2], mb[0], mb[2]}, mi[4] = {ma[1], ma[3], mb[1], mb[3]};
;                 float hr[4], hi[4];
; #pragma unroll
;                 for (int r = 0; r < 4; ++r) { hr[r] = dppf<DPP_ROR(1)>(xs[i][r]); hi[r] = dppf<DPP_ROR(1)>(xs[i + 4][r]);
;                     if (j == 0) { Er[r] += mr[r] * hr[r] - mi[r] * hi[r]; Ei[r] += mr[r] * hi[r] + mi[r] * hr[r]; } }
;     ...
;                 SSM_SCAN_STEP(1, 1) SSM_SCAN_STEP(2, 1) SSM_SCAN_STEP(4, 1) SSM_SCAN_STEP(8, 0)
	ds_read_b128 v[16:19], v105
	ds_read_b128 v[20:23], v105 offset:1024
	ds_read_b128 v[24:27], v105 offset:16384
	ds_read_b128 v[28:31], v105 offset:17408
	v_mov_b32_dpp v65, v72 row_ror:1 row_mask:0xf bank_mask:0xf bound_ctrl:1
	v_mov_b32_dpp v64, v70 row_ror:1 row_mask:0xf bank_mask:0xf bound_ctrl:1
	s_waitcnt vmcnt(3) lgkmcnt(3)
	v_mfma_f32_16x16x32_bf16 v[16:19], v[16:19], v[12:15], 0
	s_waitcnt vmcnt(2) lgkmcnt(2)
	v_mfma_f32_16x16x32_bf16 v[16:19], v[20:23], v[4:7], v[16:19]
	ds_read_b128 v[20:23], v105 offset:2048
	s_waitcnt lgkmcnt(2)
	v_mfma_f32_16x16x32_bf16 v[24:27], v[24:27], v[12:15], 0
	s_waitcnt lgkmcnt(1)
	v_mfma_f32_16x16x32_bf16 v[24:27], v[28:31], v[4:7], v[24:27]
	ds_read_b128 v[28:31], v105 offset:18432
	ds_read_b128 v[32:35], v105 offset:3072
	ds_read_b128 v[78:81], v105 offset:19456
	s_waitcnt vmcnt(1) lgkmcnt(3)
	v_mfma_f32_16x16x32_bf16 v[16:19], v[20:23], v[8:11], v[16:19]
	ds_read_b128 v[20:23], v109
	ds_read_b128 v[82:85], v109 offset:16
	s_waitcnt lgkmcnt(1)
	v_mov_b32_e32 v72, v21
	v_mfma_f32_16x16x32_bf16 v[24:27], v[28:31], v[8:11], v[24:27]
	v_mul_f32_e64 v28, v20, v65
	v_mul_f32_e64 v29, v21, v64
	v_mov_b32_e32 v70, v20
	v_sub_f32_e32 v28, v28, v29
	s_waitcnt vmcnt(0)
	v_mfma_f32_16x16x32_bf16 v[16:19], v[32:35], v[0:3], v[16:19]
	v_mfma_f32_16x16x32_bf16 v[24:27], v[78:81], v[0:3], v[24:27]
	s_nop 6
	v_add_f32_e32 v32, v16, v28
	v_pk_mul_f32 v[28:29], v[20:21], v[64:65]
	v_cndmask_b32_e64 v16, v16, v32, s[6:7]
	v_add_f32_e32 v28, v29, v28
	v_add_f32_e32 v33, v24, v28
	v_mov_b32_dpp v29, v73 row_ror:1 row_mask:0xf bank_mask:0xf bound_ctrl:1
	v_mov_b32_dpp v28, v71 row_ror:1 row_mask:0xf bank_mask:0xf bound_ctrl:1
	v_pk_mul_f32 v[30:31], v[22:23], v[28:29] op_sel:[0,1] op_sel_hi:[1,0]
	v_pk_mul_f32 v[28:29], v[22:23], v[28:29]
	v_sub_f32_e32 v30, v30, v31
	v_add_f32_e32 v28, v29, v28
	v_add_f32_e32 v35, v28, v25
	v_mov_b32_dpp v29, v76 row_ror:1 row_mask:0xf bank_mask:0xf bound_ctrl:1
	v_mov_b32_dpp v28, v74 row_ror:1 row_mask:0xf bank_mask:0xf bound_ctrl:1
	v_add_f32_e32 v34, v30, v17
	s_waitcnt lgkmcnt(0)
	v_pk_mul_f32 v[30:31], v[82:83], v[28:29] op_sel:[0,1] op_sel_hi:[1,0]
	v_pk_mul_f32 v[28:29], v[82:83], v[28:29]
	v_sub_f32_e32 v30, v30, v31
	v_add_f32_e32 v28, v29, v28
	v_add_f32_e32 v65, v28, v26
	v_mov_b32_dpp v29, v77 row_ror:1 row_mask:0xf bank_mask:0xf bound_ctrl:1
	v_mov_b32_dpp v28, v75 row_ror:1 row_mask:0xf bank_mask:0xf bound_ctrl:1
	v_add_f32_e32 v64, v30, v18
	v_pk_mul_f32 v[30:31], v[84:85], v[28:29] op_sel:[0,1] op_sel_hi:[1,0]
	v_pk_mul_f32 v[28:29], v[84:85], v[28:29]
	v_sub_f32_e32 v30, v30, v31
	v_add_f32_e32 v28, v29, v28
	v_cndmask_b32_e64 v25, v25, v35, s[6:7]
	v_cndmask_b32_e64 v24, v24, v33, s[6:7]
	v_add_f32_e32 v30, v30, v19
	v_add_f32_e32 v28, v28, v27
	v_cndmask_b32_e64 v17, v17, v34, s[6:7]
	v_mov_b32_dpp v32, v24 row_shr:1 row_mask:0xf bank_mask:0xf bound_ctrl:1
	v_mov_b32_dpp v33, v25 row_shr:1 row_mask:0xf bank_mask:0xf bound_ctrl:1
	v_mov_b32_e32 v73, v23
	v_cndmask_b32_e64 v29, v27, v28, s[6:7]
	v_cndmask_b32_e64 v28, v26, v65, s[6:7]
	v_cndmask_b32_e64 v27, v19, v30, s[6:7]
	v_cndmask_b32_e64 v26, v18, v64, s[6:7]
	v_mov_b32_dpp v30, v16 row_shr:1 row_mask:0xf bank_mask:0xf bound_ctrl:1
	v_mov_b32_dpp v31, v17 row_shr:1 row_mask:0xf bank_mask:0xf bound_ctrl:1
	v_mov_b32_e32 v71, v22
	v_pk_mul_f32 v[18:19], v[72:73], v[32:33]
	v_pk_mul_f32 v[32:33], v[70:71], v[32:33]
	v_pk_fma_f32 v[18:19], v[70:71], v[30:31], v[18:19] neg_lo:[0,0,1] neg_hi:[0,0,1]
	v_pk_fma_f32 v[30:31], v[72:73], v[30:31], v[32:33]
	v_pk_add_f32 v[74:75], v[18:19], v[16:17]
	v_pk_mul_f32 v[16:17], v[22:23], v[22:23]
	v_pk_mul_f32 v[18:19], v[20:21], v[20:21]
	v_mov_b32_e32 v21, v16
	v_mov_b32_e32 v20, v18
	v_mov_b32_e32 v16, v19
	v_pk_add_f32 v[20:21], v[20:21], v[16:17] neg_lo:[0,1] neg_hi:[0,1]
	v_pk_add_f32 v[16:17], v[70:71], v[70:71]
	v_pk_add_f32 v[24:25], v[30:31], v[24:25]
	v_pk_mul_f32 v[22:23], v[72:73], v[16:17]
	v_mov_b32_dpp v76, v74 row_shr:2 row_mask:0xf bank_mask:0xf bound_ctrl:1
	v_mov_b32_dpp v30, v24 row_shr:2 row_mask:0xf bank_mask:0xf bound_ctrl:1
	v_mov_b32_dpp v31, v25 row_shr:2 row_mask:0xf bank_mask:0xf bound_ctrl:1
	v_mov_b32_dpp v77, v75 row_shr:2 row_mask:0xf bank_mask:0xf bound_ctrl:1
	v_pk_mul_f32 v[16:17], v[22:23], v[22:23]
	v_pk_mul_f32 v[32:33], v[22:23], v[30:31]
	v_pk_fma_f32 v[16:17], v[20:21], v[20:21], v[16:17] neg_lo:[0,0,1] neg_hi:[0,0,1]
	v_pk_add_f32 v[18:19], v[20:21], v[20:21]
	v_pk_fma_f32 v[32:33], v[20:21], v[76:77], v[32:33] neg_lo:[0,0,1] neg_hi:[0,0,1]
	v_pk_mul_f32 v[20:21], v[20:21], v[30:31]
	v_pk_mul_f32 v[18:19], v[22:23], v[18:19]
	v_pk_fma_f32 v[20:21], v[22:23], v[76:77], v[20:21]
	v_pk_add_f32 v[32:33], v[32:33], v[74:75]
	v_pk_add_f32 v[22:23], v[24:25], v[20:21]
	v_mov_b32_dpp v64, v28 row_shr:1 row_mask:0xf bank_mask:0xf bound_ctrl:1
	v_mov_b32_dpp v24, v32 row_shr:4 row_mask:0xf bank_mask:0xf bound_ctrl:1
	v_mov_b32_dpp v30, v22 row_shr:4 row_mask:0xf bank_mask:0xf bound_ctrl:1
	v_mov_b32_dpp v31, v23 row_shr:4 row_mask:0xf bank_mask:0xf bound_ctrl:1
	v_mov_b32_dpp v25, v33 row_shr:4 row_mask:0xf bank_mask:0xf bound_ctrl:1
	v_pk_mul_f32 v[20:21], v[18:19], v[30:31]
	v_pk_mul_f32 v[30:31], v[16:17], v[30:31]
	v_pk_fma_f32 v[20:21], v[16:17], v[24:25], v[20:21] neg_lo:[0,0,1] neg_hi:[0,0,1]
	v_mov_b32_dpp v65, v29 row_shr:1 row_mask:0xf bank_mask:0xf bound_ctrl:1
	v_pk_add_f32 v[20:21], v[32:33], v[20:21]
	v_pk_fma_f32 v[24:25], v[18:19], v[24:25], v[30:31]
	v_mov_b32_e32 v32, v83
	v_mov_b32_e32 v33, v85
	v_mov_b32_dpp v34, v26 row_shr:1 row_mask:0xf bank_mask:0xf bound_ctrl:1
	v_mov_b32_dpp v35, v27 row_shr:1 row_mask:0xf bank_mask:0xf bound_ctrl:1
; #define SSM_SCAN_STEP(D, SQ) { _Pragma("unroll") for (int r = 0; r < 4; ++r) { \
;                     const float sr = dppf<DPP_SHR(D)>(Er[r]), si = dppf<DPP_SHR(D)>(Ei[r]); \
;                     Er[r] += mr[r] * sr - mi[r] * si; Ei[r] += mr[r] * si + mi[r] * sr; \
;                     if (SQ) { const float nr = mr[r] * mr[r] - mi[r] * mi[r], ni = 2.f * mr[r] * mi[r]; mr[r] = nr; mi[r] = ni; } } }
; template <bool PASS2>
; __device__ __forceinline__ void ssm_phase(const Params& p, const Frame& F0) {
;     ...
;                 const f32x4 ma = m1t[8 * i], mb = m1t[8 * i + 1];
;                 float mr[4] = {ma[0], ma[2], mb[0], mb[2]}, mi[4] = {ma[1], ma[3], mb[1], mb[3]};
;                 float hr[4], hi[4];
; #pragma unroll
;                 for (int r = 0; r < 4; ++r) { hr[r] = dppf<DPP_ROR(1)>(xs[i][r]); hi[r] = dppf<DPP_ROR(1)>(xs[i + 4][r]);
;                     if (j == 0) { Er[r] += mr[r] * hr[r] - mi[r] * hi[r]; Ei[r] += mr[r] * hi[r] + mi[r] * hr[r]; } }
;     ...
;                 SSM_SCAN_STEP(1, 1) SSM_SCAN_STEP(2, 1) SSM_SCAN_STEP(4, 1) SSM_SCAN_STEP(8, 0)
	v_pk_add_f32 v[22:23], v[22:23], v[24:25]
	v_mov_b32_e32 v30, v82
	v_mov_b32_e32 v31, v84
	v_pk_mul_f32 v[24:25], v[32:33], v[64:65]
	s_nop 0
	v_pk_fma_f32 v[24:25], v[30:31], v[34:35], v[24:25] neg_lo:[0,0,1] neg_hi:[0,0,1]
	s_nop 0
	v_pk_add_f32 v[70:71], v[24:25], v[26:27]
	v_pk_mul_f32 v[24:25], v[84:85], v[84:85]
	v_pk_mul_f32 v[26:27], v[82:83], v[82:83]
	v_mov_b32_e32 v73, v24
	v_mov_b32_e32 v72, v26
	v_mov_b32_e32 v24, v27
	v_pk_add_f32 v[72:73], v[72:73], v[24:25] neg_lo:[0,1] neg_hi:[0,1]
	v_pk_add_f32 v[24:25], v[30:31], v[30:31]
	v_pk_mul_f32 v[30:31], v[30:31], v[64:65]
	v_pk_mul_f32 v[74:75], v[32:33], v[24:25]
	v_pk_fma_f32 v[30:31], v[32:33], v[34:35], v[30:31]
	v_mov_b32_dpp v76, v70 row_shr:2 row_mask:0xf bank_mask:0xf bound_ctrl:1
	v_pk_add_f32 v[28:29], v[30:31], v[28:29]
	v_mov_b32_dpp v77, v71 row_shr:2 row_mask:0xf bank_mask:0xf bound_ctrl:1
	v_pk_add_f32 v[26:27], v[72:73], v[72:73]
	v_mov_b32_dpp v30, v28 row_shr:2 row_mask:0xf bank_mask:0xf bound_ctrl:1
	v_mov_b32_dpp v31, v29 row_shr:2 row_mask:0xf bank_mask:0xf bound_ctrl:1
	v_pk_mul_f32 v[32:33], v[74:75], v[30:31]
	v_pk_mul_f32 v[30:31], v[72:73], v[30:31]
	v_pk_fma_f32 v[32:33], v[72:73], v[76:77], v[32:33] neg_lo:[0,0,1] neg_hi:[0,0,1]
	v_pk_fma_f32 v[30:31], v[74:75], v[76:77], v[30:31]
	v_pk_mul_f32 v[24:25], v[74:75], v[74:75]
	v_pk_add_f32 v[30:31], v[28:29], v[30:31]
	v_pk_mul_f32 v[26:27], v[74:75], v[26:27]
	v_pk_add_f32 v[32:33], v[70:71], v[32:33]
	v_mov_b32_dpp v64, v30 row_shr:4 row_mask:0xf bank_mask:0xf bound_ctrl:1
	v_mov_b32_dpp v65, v31 row_shr:4 row_mask:0xf bank_mask:0xf bound_ctrl:1
	v_pk_fma_f32 v[24:25], v[72:73], v[72:73], v[24:25] neg_lo:[0,0,1] neg_hi:[0,0,1]
	v_mov_b32_dpp v34, v32 row_shr:4 row_mask:0xf bank_mask:0xf bound_ctrl:1
	v_mov_b32_dpp v35, v33 row_shr:4 row_mask:0xf bank_mask:0xf bound_ctrl:1
	v_pk_mul_f32 v[28:29], v[26:27], v[64:65]
	s_nop 0
	v_pk_fma_f32 v[28:29], v[24:25], v[34:35], v[28:29] neg_lo:[0,0,1] neg_hi:[0,0,1]
	s_nop 0
	v_pk_add_f32 v[28:29], v[32:33], v[28:29]
	v_pk_mul_f32 v[32:33], v[24:25], v[64:65]
	v_mov_b32_dpp v64, v22 row_shr:8 row_mask:0xf bank_mask:0xf bound_ctrl:1
	v_pk_fma_f32 v[32:33], v[26:27], v[34:35], v[32:33]
	v_mov_b32_dpp v65, v23 row_shr:8 row_mask:0xf bank_mask:0xf bound_ctrl:1
	v_pk_add_f32 v[32:33], v[30:31], v[32:33]
	v_mov_b32_dpp v30, v20 row_shr:8 row_mask:0xf bank_mask:0xf bound_ctrl:1
	v_mov_b32_dpp v31, v21 row_shr:8 row_mask:0xf bank_mask:0xf bound_ctrl:1
	v_mov_b32_dpp v34, v28 row_shr:8 row_mask:0xf bank_mask:0xf bound_ctrl:1
	v_mov_b32_dpp v70, v32 row_shr:8 row_mask:0xf bank_mask:0xf bound_ctrl:1
	v_mov_b32_dpp v35, v29 row_shr:8 row_mask:0xf bank_mask:0xf bound_ctrl:1
	v_mov_b32_dpp v71, v33 row_shr:8 row_mask:0xf bank_mask:0xf bound_ctrl:1
	ds_read_b128 v[72:75], v105 offset:4096
	ds_read_b128 v[76:79], v105 offset:5120
	ds_read_b128 v[80:83], v105 offset:20480
	ds_read_b128 v[84:87], v105 offset:21504
	v_mov_b32_dpp v101, v62 row_ror:1 row_mask:0xf bank_mask:0xf bound_ctrl:1
	v_mov_b32_dpp v100, v60 row_ror:1 row_mask:0xf bank_mask:0xf bound_ctrl:1
	s_waitcnt lgkmcnt(3)
	v_mfma_f32_16x16x32_bf16 v[72:75], v[72:75], v[12:15], 0
	v_mov_b32_dpp v63, v63 row_ror:1 row_mask:0xf bank_mask:0xf bound_ctrl:1
	v_mov_b32_dpp v62, v61 row_ror:1 row_mask:0xf bank_mask:0xf bound_ctrl:1
	s_waitcnt lgkmcnt(2)
	v_mfma_f32_16x16x32_bf16 v[72:75], v[76:79], v[4:7], v[72:75]
	ds_read_b128 v[76:79], v105 offset:6144
	s_waitcnt lgkmcnt(2)
	v_mfma_f32_16x16x32_bf16 v[80:83], v[80:83], v[12:15], 0
	s_waitcnt lgkmcnt(1)
	v_mfma_f32_16x16x32_bf16 v[80:83], v[84:87], v[4:7], v[80:83]
	ds_read_b128 v[84:87], v105 offset:22528
	ds_read_b128 v[88:91], v105 offset:7168
	ds_read_b128 v[92:95], v105 offset:23552
	s_waitcnt lgkmcnt(3)
	v_mfma_f32_16x16x32_bf16 v[72:75], v[76:79], v[8:11], v[72:75]
	ds_read_b128 v[76:79], v109 offset:128
	ds_read_b128 v[96:99], v109 offset:144
	s_waitcnt lgkmcnt(4)
	v_mfma_f32_16x16x32_bf16 v[80:83], v[84:87], v[8:11], v[80:83]
	s_waitcnt lgkmcnt(1)
	v_pk_mul_f32 v[84:85], v[76:77], v[100:101] op_sel:[0,1] op_sel_hi:[1,0]
	s_nop 0
	v_sub_f32_e32 v60, v84, v85
	v_mfma_f32_16x16x32_bf16 v[72:75], v[88:91], v[0:3], v[72:75]
	v_mul_f32_e64 v84, v76, v100
	v_mul_f32_e64 v85, v77, v101
	v_mov_b32_e32 v88, v77
	v_mov_b32_e32 v89, v79
	v_mfma_f32_16x16x32_bf16 v[80:83], v[92:95], v[0:3], v[80:83]
	s_nop 2
	v_add_f32_e32 v86, v72, v60
	v_add_f32_e32 v60, v85, v84
	s_nop 2
	v_add_f32_e32 v84, v80, v60
	v_pk_mul_f32 v[60:61], v[78:79], v[62:63] op_sel:[0,1] op_sel_hi:[1,0]
	s_nop 0
	v_sub_f32_e32 v60, v60, v61
	v_add_f32_e32 v85, v60, v73
	v_pk_mul_f32 v[60:61], v[78:79], v[62:63]
	s_nop 0
	v_add_f32_e32 v60, v61, v60
	v_add_f32_e32 v87, v60, v81
	v_mov_b32_dpp v61, v68 row_ror:1 row_mask:0xf bank_mask:0xf bound_ctrl:1
	v_mov_b32_dpp v60, v66 row_ror:1 row_mask:0xf bank_mask:0xf bound_ctrl:1
	s_waitcnt lgkmcnt(0)
; #define SSM_SCAN_STEP(D, SQ) { _Pragma("unroll") for (int r = 0; r < 4; ++r) { \
;                     const float sr = dppf<DPP_SHR(D)>(Er[r]), si = dppf<DPP_SHR(D)>(Ei[r]); \
;                     Er[r] += mr[r] * sr - mi[r] * si; Ei[r] += mr[r] * si + mi[r] * sr; \
;                     if (SQ) { const float nr = mr[r] * mr[r] - mi[r] * mi[r], ni = 2.f * mr[r] * mi[r]; mr[r] = nr; mi[r] = ni; } } }
; template <bool PASS2>
; __device__ __forceinline__ void ssm_phase(const Params& p, const Frame& F0) {
;     ...
;                 const f32x4 ma = m1t[8 * i], mb = m1t[8 * i + 1];
;                 float mr[4] = {ma[0], ma[2], mb[0], mb[2]}, mi[4] = {ma[1], ma[3], mb[1], mb[3]};
;                 float hr[4], hi[4];
; #pragma unroll
;                 for (int r = 0; r < 4; ++r) { hr[r] = dppf<DPP_ROR(1)>(xs[i][r]); hi[r] = dppf<DPP_ROR(1)>(xs[i + 4][r]);
;                     if (j == 0) { Er[r] += mr[r] * hr[r] - mi[r] * hi[r]; Ei[r] += mr[r] * hi[r] + mi[r] * hr[r]; } }
;     ...
;                 SSM_SCAN_STEP(1, 1) SSM_SCAN_STEP(2, 1) SSM_SCAN_STEP(4, 1) SSM_SCAN_STEP(8, 0)
	v_pk_mul_f32 v[62:63], v[96:97], v[60:61] op_sel:[0,1] op_sel_hi:[1,0]
	v_pk_mul_f32 v[60:61], v[96:97], v[60:61]
	v_sub_f32_e32 v62, v62, v63
	v_add_f32_e32 v60, v61, v60
	v_add_f32_e32 v66, v60, v82
	v_mov_b32_dpp v61, v69 row_ror:1 row_mask:0xf bank_mask:0xf bound_ctrl:1
	v_mov_b32_dpp v60, v67 row_ror:1 row_mask:0xf bank_mask:0xf bound_ctrl:1
	v_add_f32_e32 v68, v62, v74
	v_pk_mul_f32 v[62:63], v[98:99], v[60:61] op_sel:[0,1] op_sel_hi:[1,0]
	v_pk_mul_f32 v[60:61], v[98:99], v[60:61]
	v_sub_f32_e32 v62, v62, v63
	v_add_f32_e32 v60, v61, v60
	v_add_f32_e32 v60, v60, v83
	v_cndmask_b32_e64 v82, v82, v66, s[6:7]
	v_cndmask_b32_e64 v67, v81, v87, s[6:7]
	v_cndmask_b32_e64 v66, v80, v84, s[6:7]
	v_add_f32_e32 v62, v62, v75
	v_cndmask_b32_e64 v83, v83, v60, s[6:7]
	v_cndmask_b32_e64 v61, v73, v85, s[6:7]
	v_cndmask_b32_e64 v60, v72, v86, s[6:7]
	v_mov_b32_dpp v72, v66 row_shr:1 row_mask:0xf bank_mask:0xf bound_ctrl:1
	v_mov_b32_dpp v73, v67 row_shr:1 row_mask:0xf bank_mask:0xf bound_ctrl:1
	v_cndmask_b32_e64 v75, v75, v62, s[6:7]
	v_cndmask_b32_e64 v74, v74, v68, s[6:7]
	v_mov_b32_dpp v68, v60 row_shr:1 row_mask:0xf bank_mask:0xf bound_ctrl:1
	v_mov_b32_dpp v69, v61 row_shr:1 row_mask:0xf bank_mask:0xf bound_ctrl:1
	v_mov_b32_e32 v86, v76
	v_mov_b32_e32 v87, v78
	v_pk_mul_f32 v[62:63], v[88:89], v[72:73]
	v_pk_mul_f32 v[72:73], v[86:87], v[72:73]
	v_pk_fma_f32 v[62:63], v[86:87], v[68:69], v[62:63] neg_lo:[0,0,1] neg_hi:[0,0,1]
	v_pk_fma_f32 v[68:69], v[88:89], v[68:69], v[72:73]
	v_pk_add_f32 v[90:91], v[62:63], v[60:61]
	v_pk_mul_f32 v[60:61], v[78:79], v[78:79]
	v_pk_mul_f32 v[62:63], v[76:77], v[76:77]
	v_mov_b32_e32 v77, v60
	v_mov_b32_e32 v76, v62
	v_mov_b32_e32 v60, v63
	v_pk_add_f32 v[76:77], v[76:77], v[60:61] neg_lo:[0,1] neg_hi:[0,1]
	v_pk_add_f32 v[60:61], v[86:87], v[86:87]
	v_pk_add_f32 v[66:67], v[68:69], v[66:67]
	v_pk_mul_f32 v[78:79], v[88:89], v[60:61]
	v_mov_b32_dpp v92, v90 row_shr:2 row_mask:0xf bank_mask:0xf bound_ctrl:1
	v_mov_b32_dpp v68, v66 row_shr:2 row_mask:0xf bank_mask:0xf bound_ctrl:1
	v_mov_b32_dpp v69, v67 row_shr:2 row_mask:0xf bank_mask:0xf bound_ctrl:1
	v_mov_b32_dpp v93, v91 row_shr:2 row_mask:0xf bank_mask:0xf bound_ctrl:1
	v_pk_mul_f32 v[72:73], v[78:79], v[68:69]
	v_pk_mul_f32 v[68:69], v[76:77], v[68:69]
	v_pk_add_f32 v[62:63], v[76:77], v[76:77]
	v_pk_fma_f32 v[68:69], v[78:79], v[92:93], v[68:69]
	v_pk_fma_f32 v[72:73], v[76:77], v[92:93], v[72:73] neg_lo:[0,0,1] neg_hi:[0,0,1]
	v_pk_add_f32 v[68:69], v[66:67], v[68:69]
	v_pk_mul_f32 v[60:61], v[78:79], v[78:79]
	v_pk_mul_f32 v[62:63], v[78:79], v[62:63]
	v_pk_add_f32 v[72:73], v[72:73], v[90:91]
	v_mov_b32_dpp v78, v68 row_shr:4 row_mask:0xf bank_mask:0xf bound_ctrl:1
	v_mov_b32_dpp v79, v69 row_shr:4 row_mask:0xf bank_mask:0xf bound_ctrl:1
	v_pk_fma_f32 v[60:61], v[76:77], v[76:77], v[60:61] neg_lo:[0,0,1] neg_hi:[0,0,1]
	v_mov_b32_dpp v76, v72 row_shr:4 row_mask:0xf bank_mask:0xf bound_ctrl:1
	v_mov_b32_dpp v77, v73 row_shr:4 row_mask:0xf bank_mask:0xf bound_ctrl:1
	v_pk_mul_f32 v[66:67], v[62:63], v[78:79]
	v_mov_b32_dpp v84, v82 row_shr:1 row_mask:0xf bank_mask:0xf bound_ctrl:1
	v_pk_fma_f32 v[66:67], v[60:61], v[76:77], v[66:67] neg_lo:[0,0,1] neg_hi:[0,0,1]
	v_mov_b32_dpp v85, v83 row_shr:1 row_mask:0xf bank_mask:0xf bound_ctrl:1
	v_pk_add_f32 v[66:67], v[72:73], v[66:67]
	v_pk_mul_f32 v[72:73], v[60:61], v[78:79]
	v_mov_b32_e32 v78, v97
	v_pk_fma_f32 v[72:73], v[62:63], v[76:77], v[72:73]
	v_mov_b32_e32 v79, v99
	v_mov_b32_dpp v80, v74 row_shr:1 row_mask:0xf bank_mask:0xf bound_ctrl:1
	v_mov_b32_dpp v81, v75 row_shr:1 row_mask:0xf bank_mask:0xf bound_ctrl:1
	v_pk_add_f32 v[68:69], v[68:69], v[72:73]
	v_mov_b32_e32 v76, v96
	v_mov_b32_e32 v77, v98
	v_pk_mul_f32 v[72:73], v[78:79], v[84:85]
	s_nop 0
	v_pk_fma_f32 v[72:73], v[76:77], v[80:81], v[72:73] neg_lo:[0,0,1] neg_hi:[0,0,1]
	s_nop 0
	v_pk_add_f32 v[86:87], v[72:73], v[74:75]
	v_pk_mul_f32 v[72:73], v[98:99], v[98:99]
	v_pk_mul_f32 v[74:75], v[96:97], v[96:97]
	v_mov_b32_e32 v89, v72
	v_mov_b32_e32 v88, v74
	v_mov_b32_e32 v72, v75
	v_pk_add_f32 v[88:89], v[88:89], v[72:73] neg_lo:[0,1] neg_hi:[0,1]
	v_pk_add_f32 v[72:73], v[76:77], v[76:77]
	v_pk_mul_f32 v[76:77], v[76:77], v[84:85]
	v_pk_mul_f32 v[90:91], v[78:79], v[72:73]
	v_pk_fma_f32 v[76:77], v[78:79], v[80:81], v[76:77]
	v_mov_b32_dpp v92, v86 row_shr:2 row_mask:0xf bank_mask:0xf bound_ctrl:1
	v_pk_add_f32 v[76:77], v[76:77], v[82:83]
	v_mov_b32_dpp v93, v87 row_shr:2 row_mask:0xf bank_mask:0xf bound_ctrl:1
	v_pk_add_f32 v[74:75], v[88:89], v[88:89]
	v_mov_b32_dpp v78, v76 row_shr:2 row_mask:0xf bank_mask:0xf bound_ctrl:1
	v_mov_b32_dpp v79, v77 row_shr:2 row_mask:0xf bank_mask:0xf bound_ctrl:1
	v_pk_mul_f32 v[80:81], v[90:91], v[78:79]
	v_pk_mul_f32 v[78:79], v[88:89], v[78:79]
	v_pk_fma_f32 v[80:81], v[88:89], v[92:93], v[80:81] neg_lo:[0,0,1] neg_hi:[0,0,1]
	v_pk_fma_f32 v[78:79], v[90:91], v[92:93], v[78:79]
	v_pk_mul_f32 v[72:73], v[90:91], v[90:91]
	v_pk_add_f32 v[78:79], v[76:77], v[78:79]
	v_pk_mul_f32 v[74:75], v[90:91], v[74:75]
	v_pk_add_f32 v[80:81], v[86:87], v[80:81]
	v_mov_b32_dpp v84, v78 row_shr:4 row_mask:0xf bank_mask:0xf bound_ctrl:1
	v_mov_b32_dpp v85, v79 row_shr:4 row_mask:0xf bank_mask:0xf bound_ctrl:1
	v_pk_fma_f32 v[72:73], v[88:89], v[88:89], v[72:73] neg_lo:[0,0,1] neg_hi:[0,0,1]
	v_mov_b32_dpp v82, v80 row_shr:4 row_mask:0xf bank_mask:0xf bound_ctrl:1
	v_mov_b32_dpp v83, v81 row_shr:4 row_mask:0xf bank_mask:0xf bound_ctrl:1
	v_pk_mul_f32 v[76:77], v[74:75], v[84:85]
	s_nop 0
	v_pk_fma_f32 v[76:77], v[72:73], v[82:83], v[76:77] neg_lo:[0,0,1] neg_hi:[0,0,1]
	s_nop 0
	v_pk_add_f32 v[76:77], v[80:81], v[76:77]
	v_pk_mul_f32 v[80:81], v[72:73], v[84:85]
	v_mov_b32_dpp v84, v68 row_shr:8 row_mask:0xf bank_mask:0xf bound_ctrl:1
	v_pk_fma_f32 v[80:81], v[74:75], v[82:83], v[80:81]
	v_mov_b32_dpp v85, v69 row_shr:8 row_mask:0xf bank_mask:0xf bound_ctrl:1
	v_pk_add_f32 v[80:81], v[78:79], v[80:81]
	v_mov_b32_dpp v78, v66 row_shr:8 row_mask:0xf bank_mask:0xf bound_ctrl:1
	v_mov_b32_dpp v79, v67 row_shr:8 row_mask:0xf bank_mask:0xf bound_ctrl:1
	v_mov_b32_dpp v82, v76 row_shr:8 row_mask:0xf bank_mask:0xf bound_ctrl:1
	v_mov_b32_dpp v86, v80 row_shr:8 row_mask:0xf bank_mask:0xf bound_ctrl:1
	v_mov_b32_dpp v83, v77 row_shr:8 row_mask:0xf bank_mask:0xf bound_ctrl:1
	v_mov_b32_dpp v87, v81 row_shr:8 row_mask:0xf bank_mask:0xf bound_ctrl:1
	ds_read_b128 v[88:91], v105 offset:8192
	ds_read_b128 v[92:95], v105 offset:9216
	ds_read_b128 v[96:99], v105 offset:24576
	ds_read_b128 v[100:103], v105 offset:25600
	v_mov_b32_dpp v123, v54 row_ror:1 row_mask:0xf bank_mask:0xf bound_ctrl:1
	v_mov_b32_dpp v122, v52 row_ror:1 row_mask:0xf bank_mask:0xf bound_ctrl:1
	s_waitcnt lgkmcnt(3)
; #define SSM_SCAN_STEP(D, SQ) { _Pragma("unroll") for (int r = 0; r < 4; ++r) { \
;                     const float sr = dppf<DPP_SHR(D)>(Er[r]), si = dppf<DPP_SHR(D)>(Ei[r]); \
;                     Er[r] += mr[r] * sr - mi[r] * si; Ei[r] += mr[r] * si + mi[r] * sr; \
;                     if (SQ) { const float nr = mr[r] * mr[r] - mi[r] * mi[r], ni = 2.f * mr[r] * mi[r]; mr[r] = nr; mi[r] = ni; } } }
; template <bool PASS2>
; __device__ __forceinline__ void ssm_phase(const Params& p, const Frame& F0) {
;     ...
;             for (int i = 0; i < 4; ++i) {
;                 __builtin_amdgcn_sched_barrier(0);
;                 f32x4 Er = (f32x4){0.f, 0.f, 0.f, 0.f}, Ei = Er;
; #pragma unroll
;                 for (int ks = 0; ks < 4; ++ks) { Er = __builtin_amdgcn_mfma_f32_16x16x32_bf16(frag[(i * 4 + ks) * 64], uf[ks], Er, 0, 0, 0);
;                                                  Ei = __builtin_amdgcn_mfma_f32_16x16x32_bf16(frag[((i + 4) * 4 + ks) * 64], uf[ks], Ei, 0, 0, 0); }
;                 const f32x4 ma = m1t[8 * i], mb = m1t[8 * i + 1];
;                 float mr[4] = {ma[0], ma[2], mb[0], mb[2]}, mi[4] = {ma[1], ma[3], mb[1], mb[3]};
;                 float hr[4], hi[4];
; #pragma unroll
;                 for (int r = 0; r < 4; ++r) { hr[r] = dppf<DPP_ROR(1)>(xs[i][r]); hi[r] = dppf<DPP_ROR(1)>(xs[i + 4][r]);
;                     if (j == 0) { Er[r] += mr[r] * hr[r] - mi[r] * hi[r]; Ei[r] += mr[r] * hi[r] + mi[r] * hr[r]; } }
;     ...
;                 SSM_SCAN_STEP(1, 1) SSM_SCAN_STEP(2, 1) SSM_SCAN_STEP(4, 1) SSM_SCAN_STEP(8, 0)
	v_mfma_f32_16x16x32_bf16 v[88:91], v[88:91], v[12:15], 0
	v_mov_b32_dpp v55, v55 row_ror:1 row_mask:0xf bank_mask:0xf bound_ctrl:1
	v_mov_b32_dpp v54, v53 row_ror:1 row_mask:0xf bank_mask:0xf bound_ctrl:1
	s_waitcnt lgkmcnt(2)
	v_mfma_f32_16x16x32_bf16 v[88:91], v[92:95], v[4:7], v[88:91]
	ds_read_b128 v[92:95], v105 offset:10240
	s_waitcnt lgkmcnt(2)
	v_mfma_f32_16x16x32_bf16 v[96:99], v[96:99], v[12:15], 0
	s_waitcnt lgkmcnt(1)
	v_mfma_f32_16x16x32_bf16 v[96:99], v[100:103], v[4:7], v[96:99]
	ds_read_b128 v[100:103], v105 offset:26624
	ds_read_b128 v[110:113], v105 offset:11264
	ds_read_b128 v[114:117], v105 offset:27648
	s_waitcnt lgkmcnt(3)
	v_mfma_f32_16x16x32_bf16 v[88:91], v[92:95], v[8:11], v[88:91]
	ds_read_b128 v[92:95], v109 offset:256
	ds_read_b128 v[118:121], v109 offset:272
	s_waitcnt lgkmcnt(4)
	v_mfma_f32_16x16x32_bf16 v[96:99], v[100:103], v[8:11], v[96:99]
	s_waitcnt lgkmcnt(1)
	v_pk_mul_f32 v[100:101], v[92:93], v[122:123] op_sel:[0,1] op_sel_hi:[1,0]
	s_nop 0
	v_sub_f32_e32 v52, v100, v101
	v_mfma_f32_16x16x32_bf16 v[88:91], v[110:113], v[0:3], v[88:91]
	v_mul_f32_e64 v100, v92, v122
	v_mul_f32_e64 v101, v93, v123
	v_mov_b32_e32 v110, v93
	v_mov_b32_e32 v111, v95
	v_mfma_f32_16x16x32_bf16 v[96:99], v[114:117], v[0:3], v[96:99]
	s_nop 2
	v_add_f32_e32 v102, v88, v52
	v_add_f32_e32 v52, v101, v100
	s_nop 2
	v_add_f32_e32 v100, v96, v52
	v_pk_mul_f32 v[52:53], v[94:95], v[54:55] op_sel:[0,1] op_sel_hi:[1,0]
	s_nop 0
	v_sub_f32_e32 v52, v52, v53
	v_add_f32_e32 v101, v52, v89
	v_pk_mul_f32 v[52:53], v[94:95], v[54:55]
	s_nop 0
	v_add_f32_e32 v52, v53, v52
	v_add_f32_e32 v103, v52, v97
	v_mov_b32_dpp v53, v58 row_ror:1 row_mask:0xf bank_mask:0xf bound_ctrl:1
	v_mov_b32_dpp v52, v56 row_ror:1 row_mask:0xf bank_mask:0xf bound_ctrl:1
	s_waitcnt lgkmcnt(0)
	v_pk_mul_f32 v[54:55], v[118:119], v[52:53] op_sel:[0,1] op_sel_hi:[1,0]
	v_pk_mul_f32 v[52:53], v[118:119], v[52:53]
	v_sub_f32_e32 v54, v54, v55
	v_add_f32_e32 v52, v53, v52
	v_add_f32_e32 v56, v52, v98
	v_mov_b32_dpp v53, v59 row_ror:1 row_mask:0xf bank_mask:0xf bound_ctrl:1
	v_mov_b32_dpp v52, v57 row_ror:1 row_mask:0xf bank_mask:0xf bound_ctrl:1
	v_add_f32_e32 v58, v54, v90
	v_pk_mul_f32 v[54:55], v[120:121], v[52:53] op_sel:[0,1] op_sel_hi:[1,0]
	v_pk_mul_f32 v[52:53], v[120:121], v[52:53]
	v_sub_f32_e32 v54, v54, v55
	v_add_f32_e32 v52, v53, v52
	v_add_f32_e32 v52, v52, v99
	v_cndmask_b32_e64 v98, v98, v56, s[6:7]
	v_cndmask_b32_e64 v57, v97, v103, s[6:7]
	v_cndmask_b32_e64 v56, v96, v100, s[6:7]
	v_add_f32_e32 v54, v54, v91
	v_cndmask_b32_e64 v99, v99, v52, s[6:7]
	v_cndmask_b32_e64 v53, v89, v101, s[6:7]
	v_cndmask_b32_e64 v52, v88, v102, s[6:7]
	v_mov_b32_dpp v88, v56 row_shr:1 row_mask:0xf bank_mask:0xf bound_ctrl:1
	v_mov_b32_dpp v89, v57 row_shr:1 row_mask:0xf bank_mask:0xf bound_ctrl:1
	v_cndmask_b32_e64 v91, v91, v54, s[6:7]
	v_cndmask_b32_e64 v90, v90, v58, s[6:7]
	v_mov_b32_dpp v58, v52 row_shr:1 row_mask:0xf bank_mask:0xf bound_ctrl:1
	v_mov_b32_dpp v59, v53 row_shr:1 row_mask:0xf bank_mask:0xf bound_ctrl:1
	v_mov_b32_e32 v102, v92
	v_mov_b32_e32 v103, v94
	v_pk_mul_f32 v[54:55], v[110:111], v[88:89]
	v_pk_mul_f32 v[88:89], v[102:103], v[88:89]
	v_pk_fma_f32 v[54:55], v[102:103], v[58:59], v[54:55] neg_lo:[0,0,1] neg_hi:[0,0,1]
	v_pk_fma_f32 v[58:59], v[110:111], v[58:59], v[88:89]
	v_pk_add_f32 v[112:113], v[54:55], v[52:53]
	v_pk_mul_f32 v[52:53], v[94:95], v[94:95]
	v_pk_mul_f32 v[54:55], v[92:93], v[92:93]
	v_mov_b32_e32 v93, v52
	v_mov_b32_e32 v92, v54
	v_mov_b32_e32 v52, v55
	v_pk_add_f32 v[92:93], v[92:93], v[52:53] neg_lo:[0,1] neg_hi:[0,1]
	v_pk_add_f32 v[52:53], v[102:103], v[102:103]
	v_pk_add_f32 v[56:57], v[58:59], v[56:57]
	v_pk_mul_f32 v[94:95], v[110:111], v[52:53]
	v_mov_b32_dpp v114, v112 row_shr:2 row_mask:0xf bank_mask:0xf bound_ctrl:1
	v_mov_b32_dpp v58, v56 row_shr:2 row_mask:0xf bank_mask:0xf bound_ctrl:1
	v_mov_b32_dpp v59, v57 row_shr:2 row_mask:0xf bank_mask:0xf bound_ctrl:1
	v_mov_b32_dpp v115, v113 row_shr:2 row_mask:0xf bank_mask:0xf bound_ctrl:1
	v_pk_mul_f32 v[88:89], v[94:95], v[58:59]
	v_pk_mul_f32 v[58:59], v[92:93], v[58:59]
	v_pk_add_f32 v[54:55], v[92:93], v[92:93]
	v_pk_fma_f32 v[58:59], v[94:95], v[114:115], v[58:59]
	v_pk_fma_f32 v[88:89], v[92:93], v[114:115], v[88:89] neg_lo:[0,0,1] neg_hi:[0,0,1]
	v_pk_add_f32 v[58:59], v[56:57], v[58:59]
	v_pk_mul_f32 v[52:53], v[94:95], v[94:95]
	v_pk_mul_f32 v[54:55], v[94:95], v[54:55]
	v_pk_add_f32 v[88:89], v[88:89], v[112:113]
	v_mov_b32_dpp v94, v58 row_shr:4 row_mask:0xf bank_mask:0xf bound_ctrl:1
	v_mov_b32_dpp v95, v59 row_shr:4 row_mask:0xf bank_mask:0xf bound_ctrl:1
	v_pk_fma_f32 v[52:53], v[92:93], v[92:93], v[52:53] neg_lo:[0,0,1] neg_hi:[0,0,1]
	v_mov_b32_dpp v92, v88 row_shr:4 row_mask:0xf bank_mask:0xf bound_ctrl:1
	v_mov_b32_dpp v93, v89 row_shr:4 row_mask:0xf bank_mask:0xf bound_ctrl:1
	v_pk_mul_f32 v[56:57], v[54:55], v[94:95]
	v_mov_b32_dpp v100, v98 row_shr:1 row_mask:0xf bank_mask:0xf bound_ctrl:1
	v_pk_fma_f32 v[56:57], v[52:53], v[92:93], v[56:57] neg_lo:[0,0,1] neg_hi:[0,0,1]
	v_mov_b32_dpp v101, v99 row_shr:1 row_mask:0xf bank_mask:0xf bound_ctrl:1
	v_pk_add_f32 v[56:57], v[88:89], v[56:57]
	v_pk_mul_f32 v[88:89], v[52:53], v[94:95]
	v_mov_b32_e32 v94, v119
	v_pk_fma_f32 v[88:89], v[54:55], v[92:93], v[88:89]
	v_mov_b32_e32 v95, v121
	v_mov_b32_dpp v96, v90 row_shr:1 row_mask:0xf bank_mask:0xf bound_ctrl:1
	v_mov_b32_dpp v97, v91 row_shr:1 row_mask:0xf bank_mask:0xf bound_ctrl:1
	v_pk_add_f32 v[58:59], v[58:59], v[88:89]
	v_mov_b32_e32 v92, v118
	v_mov_b32_e32 v93, v120
	v_pk_mul_f32 v[88:89], v[94:95], v[100:101]
	s_nop 0
; #define SSM_SCAN_STEP(D, SQ) { _Pragma("unroll") for (int r = 0; r < 4; ++r) { \
;                     const float sr = dppf<DPP_SHR(D)>(Er[r]), si = dppf<DPP_SHR(D)>(Ei[r]); \
;                     Er[r] += mr[r] * sr - mi[r] * si; Ei[r] += mr[r] * si + mi[r] * sr; \
;                     if (SQ) { const float nr = mr[r] * mr[r] - mi[r] * mi[r], ni = 2.f * mr[r] * mi[r]; mr[r] = nr; mi[r] = ni; } } }
; template <bool PASS2>
; __device__ __forceinline__ void ssm_phase(const Params& p, const Frame& F0) {
;     ...
;             for (int i = 0; i < 4; ++i) {
;                 __builtin_amdgcn_sched_barrier(0);
;                 f32x4 Er = (f32x4){0.f, 0.f, 0.f, 0.f}, Ei = Er;
; #pragma unroll
;                 for (int ks = 0; ks < 4; ++ks) { Er = __builtin_amdgcn_mfma_f32_16x16x32_bf16(frag[(i * 4 + ks) * 64], uf[ks], Er, 0, 0, 0);
;                                                  Ei = __builtin_amdgcn_mfma_f32_16x16x32_bf16(frag[((i + 4) * 4 + ks) * 64], uf[ks], Ei, 0, 0, 0); }
;                 const f32x4 ma = m1t[8 * i], mb = m1t[8 * i + 1];
;                 float mr[4] = {ma[0], ma[2], mb[0], mb[2]}, mi[4] = {ma[1], ma[3], mb[1], mb[3]};
;                 float hr[4], hi[4];
; #pragma unroll
;                 for (int r = 0; r < 4; ++r) { hr[r] = dppf<DPP_ROR(1)>(xs[i][r]); hi[r] = dppf<DPP_ROR(1)>(xs[i + 4][r]);
;                     if (j == 0) { Er[r] += mr[r] * hr[r] - mi[r] * hi[r]; Ei[r] += mr[r] * hi[r] + mi[r] * hr[r]; } }
;     ...
;                 SSM_SCAN_STEP(1, 1) SSM_SCAN_STEP(2, 1) SSM_SCAN_STEP(4, 1) SSM_SCAN_STEP(8, 0)
	v_pk_fma_f32 v[88:89], v[92:93], v[96:97], v[88:89] neg_lo:[0,0,1] neg_hi:[0,0,1]
	s_nop 0
	v_pk_add_f32 v[102:103], v[88:89], v[90:91]
	v_pk_mul_f32 v[88:89], v[120:121], v[120:121]
	v_pk_mul_f32 v[90:91], v[118:119], v[118:119]
	v_mov_b32_e32 v111, v88
	v_mov_b32_e32 v110, v90
	v_mov_b32_e32 v88, v91
	v_pk_add_f32 v[110:111], v[110:111], v[88:89] neg_lo:[0,1] neg_hi:[0,1]
	v_pk_add_f32 v[88:89], v[92:93], v[92:93]
	v_pk_mul_f32 v[92:93], v[92:93], v[100:101]
	v_pk_mul_f32 v[112:113], v[94:95], v[88:89]
	v_pk_fma_f32 v[92:93], v[94:95], v[96:97], v[92:93]
	v_mov_b32_dpp v114, v102 row_shr:2 row_mask:0xf bank_mask:0xf bound_ctrl:1
	v_pk_add_f32 v[92:93], v[92:93], v[98:99]
	v_mov_b32_dpp v115, v103 row_shr:2 row_mask:0xf bank_mask:0xf bound_ctrl:1
	v_pk_add_f32 v[90:91], v[110:111], v[110:111]
	v_mov_b32_dpp v94, v92 row_shr:2 row_mask:0xf bank_mask:0xf bound_ctrl:1
	v_mov_b32_dpp v95, v93 row_shr:2 row_mask:0xf bank_mask:0xf bound_ctrl:1
	v_pk_mul_f32 v[96:97], v[112:113], v[94:95]
	v_pk_mul_f32 v[94:95], v[110:111], v[94:95]
	v_pk_fma_f32 v[96:97], v[110:111], v[114:115], v[96:97] neg_lo:[0,0,1] neg_hi:[0,0,1]
	v_pk_fma_f32 v[94:95], v[112:113], v[114:115], v[94:95]
	v_pk_mul_f32 v[88:89], v[112:113], v[112:113]
	v_pk_add_f32 v[94:95], v[92:93], v[94:95]
	v_pk_mul_f32 v[90:91], v[112:113], v[90:91]
	v_pk_add_f32 v[96:97], v[102:103], v[96:97]
	v_mov_b32_dpp v100, v94 row_shr:4 row_mask:0xf bank_mask:0xf bound_ctrl:1
	v_mov_b32_dpp v101, v95 row_shr:4 row_mask:0xf bank_mask:0xf bound_ctrl:1
	v_pk_fma_f32 v[88:89], v[110:111], v[110:111], v[88:89] neg_lo:[0,0,1] neg_hi:[0,0,1]
	v_mov_b32_dpp v98, v96 row_shr:4 row_mask:0xf bank_mask:0xf bound_ctrl:1
	v_mov_b32_dpp v99, v97 row_shr:4 row_mask:0xf bank_mask:0xf bound_ctrl:1
	v_pk_mul_f32 v[92:93], v[90:91], v[100:101]
	s_nop 0
	v_pk_fma_f32 v[92:93], v[88:89], v[98:99], v[92:93] neg_lo:[0,0,1] neg_hi:[0,0,1]
	s_nop 0
	v_pk_add_f32 v[92:93], v[96:97], v[92:93]
	v_pk_mul_f32 v[96:97], v[88:89], v[100:101]
	v_mov_b32_dpp v100, v58 row_shr:8 row_mask:0xf bank_mask:0xf bound_ctrl:1
	v_pk_fma_f32 v[96:97], v[90:91], v[98:99], v[96:97]
	v_mov_b32_dpp v101, v59 row_shr:8 row_mask:0xf bank_mask:0xf bound_ctrl:1
	v_pk_add_f32 v[96:97], v[94:95], v[96:97]
	v_mov_b32_dpp v94, v56 row_shr:8 row_mask:0xf bank_mask:0xf bound_ctrl:1
	v_mov_b32_dpp v95, v57 row_shr:8 row_mask:0xf bank_mask:0xf bound_ctrl:1
	v_mov_b32_dpp v98, v92 row_shr:8 row_mask:0xf bank_mask:0xf bound_ctrl:1
	v_mov_b32_dpp v102, v96 row_shr:8 row_mask:0xf bank_mask:0xf bound_ctrl:1
	v_mov_b32_dpp v99, v93 row_shr:8 row_mask:0xf bank_mask:0xf bound_ctrl:1
	v_mov_b32_dpp v103, v97 row_shr:8 row_mask:0xf bank_mask:0xf bound_ctrl:1
	ds_read_b128 v[110:113], v105 offset:12288
	ds_read_b128 v[114:117], v105 offset:28672
	v_mov_b32_dpp v47, v47 row_ror:1 row_mask:0xf bank_mask:0xf bound_ctrl:1
	s_waitcnt lgkmcnt(1)
	v_mfma_f32_16x16x32_bf16 v[110:113], v[110:113], v[12:15], 0
	s_waitcnt lgkmcnt(0)
	v_mfma_f32_16x16x32_bf16 v[12:15], v[114:117], v[12:15], 0
	ds_read_b128 v[114:117], v105 offset:13312
	s_waitcnt lgkmcnt(0)
	v_mfma_f32_16x16x32_bf16 v[110:113], v[114:117], v[4:7], v[110:113]
	ds_read_b128 v[114:117], v105 offset:29696
	s_waitcnt lgkmcnt(0)
	v_mfma_f32_16x16x32_bf16 v[4:7], v[114:117], v[4:7], v[12:15]
	s_nop 2
	ds_read_b128 v[12:15], v105 offset:14336
	s_waitcnt lgkmcnt(0)
	v_mfma_f32_16x16x32_bf16 v[12:15], v[12:15], v[8:11], v[110:113]
	s_nop 2
	ds_read_b128 v[110:113], v105 offset:30720
	s_waitcnt lgkmcnt(0)
	v_mfma_f32_16x16x32_bf16 v[4:7], v[110:113], v[8:11], v[4:7]
	ds_read_b128 v[8:11], v105 offset:15360
	v_mov_b32_dpp v111, v46 row_ror:1 row_mask:0xf bank_mask:0xf bound_ctrl:1
	v_mov_b32_dpp v110, v44 row_ror:1 row_mask:0xf bank_mask:0xf bound_ctrl:1
	s_waitcnt lgkmcnt(0)
	v_mfma_f32_16x16x32_bf16 v[8:11], v[8:11], v[0:3], v[12:15]
	s_nop 2
	ds_read_b128 v[12:15], v105 offset:31744
	v_mov_b32_dpp v46, v45 row_ror:1 row_mask:0xf bank_mask:0xf bound_ctrl:1
	s_waitcnt lgkmcnt(0)
	v_mfma_f32_16x16x32_bf16 v[0:3], v[12:15], v[0:3], v[4:7]
	s_nop 2
	ds_read_b128 v[4:7], v109 offset:384
	ds_read_b128 v[12:15], v109 offset:400
	s_waitcnt lgkmcnt(1)
	v_pk_mul_f32 v[112:113], v[4:5], v[110:111] op_sel:[0,1] op_sel_hi:[1,0]
	s_nop 0
	v_sub_f32_e32 v44, v112, v113
	v_pk_mul_f32 v[110:111], v[4:5], v[110:111]
	v_add_f32_e32 v112, v8, v44
	v_add_f32_e32 v44, v111, v110
	v_add_f32_e32 v110, v0, v44
	v_pk_mul_f32 v[44:45], v[6:7], v[46:47] op_sel:[0,1] op_sel_hi:[1,0]
	v_mov_b32_e32 v114, v5
	v_sub_f32_e32 v44, v44, v45
	v_add_f32_e32 v111, v44, v9
	v_pk_mul_f32 v[44:45], v[6:7], v[46:47]
	v_mov_b32_e32 v115, v7
	v_add_f32_e32 v44, v45, v44
	v_add_f32_e32 v113, v44, v1
	v_mov_b32_dpp v45, v50 row_ror:1 row_mask:0xf bank_mask:0xf bound_ctrl:1
	v_mov_b32_dpp v44, v48 row_ror:1 row_mask:0xf bank_mask:0xf bound_ctrl:1
	s_waitcnt lgkmcnt(0)
; #define SSM_SCAN_STEP(D, SQ) { _Pragma("unroll") for (int r = 0; r < 4; ++r) { \
;                     const float sr = dppf<DPP_SHR(D)>(Er[r]), si = dppf<DPP_SHR(D)>(Ei[r]); \
;                     Er[r] += mr[r] * sr - mi[r] * si; Ei[r] += mr[r] * si + mi[r] * sr; \
;                     if (SQ) { const float nr = mr[r] * mr[r] - mi[r] * mi[r], ni = 2.f * mr[r] * mi[r]; mr[r] = nr; mi[r] = ni; } } }
; template <bool PASS2>
; __device__ __forceinline__ void ssm_phase(const Params& p, const Frame& F0) {
;     ...
;                 const f32x4 ma = m1t[8 * i], mb = m1t[8 * i + 1];
;                 float mr[4] = {ma[0], ma[2], mb[0], mb[2]}, mi[4] = {ma[1], ma[3], mb[1], mb[3]};
;                 float hr[4], hi[4];
; #pragma unroll
;                 for (int r = 0; r < 4; ++r) { hr[r] = dppf<DPP_ROR(1)>(xs[i][r]); hi[r] = dppf<DPP_ROR(1)>(xs[i + 4][r]);
;                     if (j == 0) { Er[r] += mr[r] * hr[r] - mi[r] * hi[r]; Ei[r] += mr[r] * hi[r] + mi[r] * hr[r]; } }
;     ...
;                 SSM_SCAN_STEP(1, 1) SSM_SCAN_STEP(2, 1) SSM_SCAN_STEP(4, 1) SSM_SCAN_STEP(8, 0)
;     ...
;         if constexpr (!PASS2) { if (j == 15) { float* wb = Wst + (size_t)((g * 2 + b) * 32 + wch) * 128;
	v_pk_mul_f32 v[46:47], v[12:13], v[44:45] op_sel:[0,1] op_sel_hi:[1,0]
	v_pk_mul_f32 v[44:45], v[12:13], v[44:45]
	v_sub_f32_e32 v46, v46, v47
	v_add_f32_e32 v44, v45, v44
	v_add_f32_e32 v50, v44, v2
	v_mov_b32_dpp v45, v51 row_ror:1 row_mask:0xf bank_mask:0xf bound_ctrl:1
	v_mov_b32_dpp v44, v49 row_ror:1 row_mask:0xf bank_mask:0xf bound_ctrl:1
	v_add_f32_e32 v48, v46, v10
	v_pk_mul_f32 v[46:47], v[14:15], v[44:45] op_sel:[0,1] op_sel_hi:[1,0]
	v_pk_mul_f32 v[44:45], v[14:15], v[44:45]
	v_sub_f32_e32 v46, v46, v47
	v_add_f32_e32 v49, v46, v11
	v_add_f32_e32 v44, v45, v44
	v_cndmask_b32_e64 v47, v1, v113, s[6:7]
	v_cndmask_b32_e64 v46, v0, v110, s[6:7]
	v_add_f32_e32 v44, v44, v3
	v_cndmask_b32_e64 v11, v11, v49, s[6:7]
	v_cndmask_b32_e64 v10, v10, v48, s[6:7]
	v_cndmask_b32_e64 v1, v9, v111, s[6:7]
	v_cndmask_b32_e64 v0, v8, v112, s[6:7]
	v_mov_b32_dpp v48, v46 row_shr:1 row_mask:0xf bank_mask:0xf bound_ctrl:1
	v_mov_b32_dpp v49, v47 row_shr:1 row_mask:0xf bank_mask:0xf bound_ctrl:1
	v_cndmask_b32_e64 v45, v3, v44, s[6:7]
	v_cndmask_b32_e64 v44, v2, v50, s[6:7]
	v_mov_b32_dpp v8, v0 row_shr:1 row_mask:0xf bank_mask:0xf bound_ctrl:1
	v_mov_b32_dpp v9, v1 row_shr:1 row_mask:0xf bank_mask:0xf bound_ctrl:1
	v_mov_b32_e32 v112, v4
	v_mov_b32_e32 v113, v6
	v_pk_mul_f32 v[2:3], v[114:115], v[48:49]
	v_pk_mul_f32 v[48:49], v[112:113], v[48:49]
	v_pk_fma_f32 v[2:3], v[112:113], v[8:9], v[2:3] neg_lo:[0,0,1] neg_hi:[0,0,1]
	v_pk_fma_f32 v[8:9], v[114:115], v[8:9], v[48:49]
	v_pk_add_f32 v[116:117], v[2:3], v[0:1]
	v_pk_mul_f32 v[0:1], v[6:7], v[6:7]
	v_pk_mul_f32 v[2:3], v[4:5], v[4:5]
	v_mov_b32_e32 v5, v0
	v_mov_b32_e32 v4, v2
	v_mov_b32_e32 v0, v3
	v_pk_add_f32 v[4:5], v[4:5], v[0:1] neg_lo:[0,1] neg_hi:[0,1]
	v_pk_add_f32 v[0:1], v[112:113], v[112:113]
	v_pk_add_f32 v[8:9], v[8:9], v[46:47]
	v_pk_mul_f32 v[6:7], v[114:115], v[0:1]
	v_mov_b32_dpp v118, v116 row_shr:2 row_mask:0xf bank_mask:0xf bound_ctrl:1
	v_mov_b32_dpp v46, v8 row_shr:2 row_mask:0xf bank_mask:0xf bound_ctrl:1
	v_mov_b32_dpp v47, v9 row_shr:2 row_mask:0xf bank_mask:0xf bound_ctrl:1
	v_mov_b32_dpp v119, v117 row_shr:2 row_mask:0xf bank_mask:0xf bound_ctrl:1
	v_pk_mul_f32 v[0:1], v[6:7], v[6:7]
	v_pk_mul_f32 v[48:49], v[6:7], v[46:47]
	v_pk_fma_f32 v[0:1], v[4:5], v[4:5], v[0:1] neg_lo:[0,0,1] neg_hi:[0,0,1]
	v_pk_add_f32 v[2:3], v[4:5], v[4:5]
	v_pk_fma_f32 v[48:49], v[4:5], v[118:119], v[48:49] neg_lo:[0,0,1] neg_hi:[0,0,1]
	v_pk_mul_f32 v[4:5], v[4:5], v[46:47]
	v_pk_mul_f32 v[2:3], v[6:7], v[2:3]
	v_pk_fma_f32 v[4:5], v[6:7], v[118:119], v[4:5]
	v_pk_add_f32 v[48:49], v[48:49], v[116:117]
	v_pk_add_f32 v[6:7], v[8:9], v[4:5]
	v_mov_b32_dpp v110, v44 row_shr:1 row_mask:0xf bank_mask:0xf bound_ctrl:1
	v_mov_b32_dpp v8, v48 row_shr:4 row_mask:0xf bank_mask:0xf bound_ctrl:1
	v_mov_b32_dpp v46, v6 row_shr:4 row_mask:0xf bank_mask:0xf bound_ctrl:1
	v_mov_b32_dpp v47, v7 row_shr:4 row_mask:0xf bank_mask:0xf bound_ctrl:1
	v_mov_b32_dpp v9, v49 row_shr:4 row_mask:0xf bank_mask:0xf bound_ctrl:1
	v_pk_mul_f32 v[4:5], v[2:3], v[46:47]
	v_pk_mul_f32 v[46:47], v[0:1], v[46:47]
	v_pk_fma_f32 v[4:5], v[0:1], v[8:9], v[4:5] neg_lo:[0,0,1] neg_hi:[0,0,1]
	v_mov_b32_dpp v111, v45 row_shr:1 row_mask:0xf bank_mask:0xf bound_ctrl:1
	v_pk_add_f32 v[4:5], v[48:49], v[4:5]
	v_pk_fma_f32 v[8:9], v[2:3], v[8:9], v[46:47]
	v_mov_b32_e32 v48, v13
	v_mov_b32_e32 v49, v15
	v_mov_b32_dpp v50, v10 row_shr:1 row_mask:0xf bank_mask:0xf bound_ctrl:1
	v_mov_b32_dpp v51, v11 row_shr:1 row_mask:0xf bank_mask:0xf bound_ctrl:1
	v_pk_add_f32 v[6:7], v[6:7], v[8:9]
	v_mov_b32_e32 v46, v12
	v_mov_b32_e32 v47, v14
	v_pk_mul_f32 v[8:9], v[48:49], v[110:111]
	s_nop 0
	v_pk_fma_f32 v[8:9], v[46:47], v[50:51], v[8:9] neg_lo:[0,0,1] neg_hi:[0,0,1]
	s_nop 0
	v_pk_add_f32 v[112:113], v[8:9], v[10:11]
	v_pk_mul_f32 v[8:9], v[14:15], v[14:15]
	v_pk_mul_f32 v[10:11], v[12:13], v[12:13]
	v_mov_b32_e32 v13, v8
	v_mov_b32_e32 v12, v10
	v_mov_b32_e32 v8, v11
	v_pk_add_f32 v[12:13], v[12:13], v[8:9] neg_lo:[0,1] neg_hi:[0,1]
	v_pk_add_f32 v[8:9], v[46:47], v[46:47]
	v_pk_mul_f32 v[46:47], v[46:47], v[110:111]
	v_pk_mul_f32 v[14:15], v[48:49], v[8:9]
	v_pk_fma_f32 v[46:47], v[48:49], v[50:51], v[46:47]
	v_mov_b32_dpp v114, v112 row_shr:2 row_mask:0xf bank_mask:0xf bound_ctrl:1
	v_pk_add_f32 v[44:45], v[46:47], v[44:45]
	v_mov_b32_dpp v115, v113 row_shr:2 row_mask:0xf bank_mask:0xf bound_ctrl:1
	v_pk_mul_f32 v[8:9], v[14:15], v[14:15]
	v_mov_b32_dpp v46, v44 row_shr:2 row_mask:0xf bank_mask:0xf bound_ctrl:1
	v_mov_b32_dpp v47, v45 row_shr:2 row_mask:0xf bank_mask:0xf bound_ctrl:1
	v_pk_mul_f32 v[48:49], v[14:15], v[46:47]
	v_pk_fma_f32 v[8:9], v[12:13], v[12:13], v[8:9] neg_lo:[0,0,1] neg_hi:[0,0,1]
	v_pk_add_f32 v[10:11], v[12:13], v[12:13]
	v_pk_fma_f32 v[48:49], v[12:13], v[114:115], v[48:49] neg_lo:[0,0,1] neg_hi:[0,0,1]
	v_pk_mul_f32 v[12:13], v[12:13], v[46:47]
	v_pk_mul_f32 v[10:11], v[14:15], v[10:11]
	v_pk_fma_f32 v[12:13], v[14:15], v[114:115], v[12:13]
	v_pk_add_f32 v[48:49], v[112:113], v[48:49]
	v_pk_add_f32 v[14:15], v[44:45], v[12:13]
	s_nop 0
	v_mov_b32_dpp v44, v48 row_shr:4 row_mask:0xf bank_mask:0xf bound_ctrl:1
	v_mov_b32_dpp v46, v14 row_shr:4 row_mask:0xf bank_mask:0xf bound_ctrl:1
	v_mov_b32_dpp v47, v15 row_shr:4 row_mask:0xf bank_mask:0xf bound_ctrl:1
	v_mov_b32_dpp v45, v49 row_shr:4 row_mask:0xf bank_mask:0xf bound_ctrl:1
	v_pk_mul_f32 v[12:13], v[10:11], v[46:47]
	v_pk_mul_f32 v[46:47], v[8:9], v[46:47]
	v_pk_fma_f32 v[12:13], v[8:9], v[44:45], v[12:13] neg_lo:[0,0,1] neg_hi:[0,0,1]
	v_pk_fma_f32 v[44:45], v[10:11], v[44:45], v[46:47]
	v_pk_add_f32 v[12:13], v[48:49], v[12:13]
	v_pk_add_f32 v[44:45], v[14:15], v[44:45]
	v_mov_b32_dpp v14, v4 row_shr:8 row_mask:0xf bank_mask:0xf bound_ctrl:1
	v_mov_b32_dpp v46, v6 row_shr:8 row_mask:0xf bank_mask:0xf bound_ctrl:1
	v_mov_b32_dpp v15, v5 row_shr:8 row_mask:0xf bank_mask:0xf bound_ctrl:1
	v_mov_b32_dpp v47, v7 row_shr:8 row_mask:0xf bank_mask:0xf bound_ctrl:1
	v_mov_b32_dpp v48, v12 row_shr:8 row_mask:0xf bank_mask:0xf bound_ctrl:1
	v_mov_b32_dpp v50, v44 row_shr:8 row_mask:0xf bank_mask:0xf bound_ctrl:1
	v_mov_b32_dpp v49, v13 row_shr:8 row_mask:0xf bank_mask:0xf bound_ctrl:1
	v_mov_b32_dpp v51, v45 row_shr:8 row_mask:0xf bank_mask:0xf bound_ctrl:1
	s_and_saveexec_b64 s[0:1], s[8:9]
	s_cbranch_execz .LBB0_520
; #define SSM_SCAN_STEP(D, SQ) { _Pragma("unroll") for (int r = 0; r < 4; ++r) { \
;                     const float sr = dppf<DPP_SHR(D)>(Er[r]), si = dppf<DPP_SHR(D)>(Ei[r]); \
;                     Er[r] += mr[r] * sr - mi[r] * si; Ei[r] += mr[r] * si + mi[r] * sr; \
;                     if (SQ) { const float nr = mr[r] * mr[r] - mi[r] * mi[r], ni = 2.f * mr[r] * mi[r]; mr[r] = nr; mi[r] = ni; } } }
; template <bool PASS2>
; __device__ __forceinline__ void ssm_phase(const Params& p, const Frame& F0) {
;     ...
;                 SSM_SCAN_STEP(1, 1) SSM_SCAN_STEP(2, 1) SSM_SCAN_STEP(4, 1) SSM_SCAN_STEP(8, 0)
;     ...
;         if constexpr (!PASS2) { if (j == 15) { float* wb = Wst + (size_t)((g * 2 + b) * 32 + wch) * 128;
; #pragma unroll
;                 for (int i = 0; i < 4; ++i) { *(f32x4*)(wb + 16 * i + 4 * gq) = xs[i]; *(f32x4*)(wb + 64 + 16 * i + 4 * gq) = xs[i + 4]; } } }
	v_pk_mul_f32 v[112:113], v[54:55], v[54:55]
	v_pk_add_f32 v[110:111], v[52:53], v[52:53]
	v_pk_mul_f32 v[116:117], v[90:91], v[90:91]
	v_pk_fma_f32 v[112:113], v[52:53], v[52:53], v[112:113] neg_lo:[0,0,1] neg_hi:[0,0,1]
	v_pk_add_f32 v[114:115], v[88:89], v[88:89]
	v_pk_mul_f32 v[110:111], v[54:55], v[110:111]
	v_pk_fma_f32 v[88:89], v[88:89], v[88:89], v[116:117] neg_lo:[0,0,1] neg_hi:[0,0,1]
	v_pk_mul_f32 v[52:53], v[112:113], v[100:101]
	v_pk_mul_f32 v[90:91], v[90:91], v[114:115]
	v_pk_mul_f32 v[54:55], v[88:89], v[102:103]
	v_pk_fma_f32 v[52:53], v[110:111], v[94:95], v[52:53]
	v_pk_fma_f32 v[54:55], v[90:91], v[98:99], v[54:55]
	v_pk_add_f32 v[52:53], v[58:59], v[52:53]
	v_pk_mul_f32 v[58:59], v[110:111], v[100:101]
	v_pk_mul_f32 v[90:91], v[90:91], v[102:103]
	v_pk_fma_f32 v[58:59], v[112:113], v[94:95], v[58:59] neg_lo:[0,0,1] neg_hi:[0,0,1]
	v_pk_fma_f32 v[88:89], v[88:89], v[98:99], v[90:91] neg_lo:[0,0,1] neg_hi:[0,0,1]
	v_pk_mul_f32 v[90:91], v[62:63], v[62:63]
	v_pk_add_f32 v[56:57], v[56:57], v[58:59]
	v_pk_add_f32 v[58:59], v[92:93], v[88:89]
	v_pk_add_f32 v[88:89], v[60:61], v[60:61]
	v_pk_mul_f32 v[94:95], v[74:75], v[74:75]
	v_pk_fma_f32 v[90:91], v[60:61], v[60:61], v[90:91] neg_lo:[0,0,1] neg_hi:[0,0,1]
	v_pk_add_f32 v[92:93], v[72:73], v[72:73]
	v_pk_mul_f32 v[88:89], v[62:63], v[88:89]
	v_pk_fma_f32 v[72:73], v[72:73], v[72:73], v[94:95] neg_lo:[0,0,1] neg_hi:[0,0,1]
	v_pk_mul_f32 v[60:61], v[90:91], v[84:85]
	v_pk_mul_f32 v[74:75], v[74:75], v[92:93]
	v_pk_mul_f32 v[62:63], v[72:73], v[86:87]
	v_pk_fma_f32 v[60:61], v[88:89], v[78:79], v[60:61]
	v_pk_fma_f32 v[62:63], v[74:75], v[82:83], v[62:63]
	v_pk_add_f32 v[60:61], v[68:69], v[60:61]
	v_pk_mul_f32 v[68:69], v[88:89], v[84:85]
	v_pk_mul_f32 v[74:75], v[74:75], v[86:87]
	v_pk_fma_f32 v[68:69], v[90:91], v[78:79], v[68:69] neg_lo:[0,0,1] neg_hi:[0,0,1]
	v_pk_fma_f32 v[72:73], v[72:73], v[82:83], v[74:75] neg_lo:[0,0,1] neg_hi:[0,0,1]
	v_pk_mul_f32 v[74:75], v[18:19], v[18:19]
	v_pk_add_f32 v[66:67], v[66:67], v[68:69]
	v_pk_add_f32 v[68:69], v[76:77], v[72:73]
	v_pk_add_f32 v[72:73], v[16:17], v[16:17]
	v_pk_mul_f32 v[78:79], v[26:27], v[26:27]
	v_pk_fma_f32 v[74:75], v[16:17], v[16:17], v[74:75] neg_lo:[0,0,1] neg_hi:[0,0,1]
	v_pk_add_f32 v[76:77], v[24:25], v[24:25]
	v_pk_mul_f32 v[72:73], v[18:19], v[72:73]
	v_pk_fma_f32 v[24:25], v[24:25], v[24:25], v[78:79] neg_lo:[0,0,1] neg_hi:[0,0,1]
	v_pk_mul_f32 v[16:17], v[74:75], v[64:65]
	v_pk_mul_f32 v[26:27], v[26:27], v[76:77]
	v_pk_mul_f32 v[18:19], v[24:25], v[70:71]
	v_pk_fma_f32 v[16:17], v[72:73], v[30:31], v[16:17]
	v_pk_fma_f32 v[18:19], v[26:27], v[34:35], v[18:19]
	v_pk_add_f32 v[16:17], v[22:23], v[16:17]
	v_pk_mul_f32 v[22:23], v[72:73], v[64:65]
	v_pk_mul_f32 v[26:27], v[26:27], v[70:71]
	v_pk_fma_f32 v[22:23], v[74:75], v[30:31], v[22:23] neg_lo:[0,0,1] neg_hi:[0,0,1]
	v_pk_fma_f32 v[24:25], v[24:25], v[34:35], v[26:27] neg_lo:[0,0,1] neg_hi:[0,0,1]
	v_pk_mul_f32 v[30:31], v[2:3], v[2:3]
	v_pk_add_f32 v[20:21], v[20:21], v[22:23]
	v_pk_add_f32 v[22:23], v[28:29], v[24:25]
	v_pk_mul_f32 v[26:27], v[10:11], v[10:11]
	v_pk_add_f32 v[28:29], v[0:1], v[0:1]
	v_pk_fma_f32 v[30:31], v[0:1], v[0:1], v[30:31] neg_lo:[0,0,1] neg_hi:[0,0,1]
	s_lshl_b32 s10, s16, 6
	s_lshl_b32 s16, s17, 5
	v_pk_add_f32 v[24:25], v[8:9], v[8:9]
	v_pk_mul_f32 v[28:29], v[2:3], v[28:29]
	v_pk_fma_f32 v[8:9], v[8:9], v[8:9], v[26:27] neg_lo:[0,0,1] neg_hi:[0,0,1]
	v_pk_mul_f32 v[0:1], v[30:31], v[46:47]
	s_add_i32 s16, s18, s16
	v_pk_mul_f32 v[10:11], v[10:11], v[24:25]
	v_pk_mul_f32 v[2:3], v[8:9], v[50:51]
	v_pk_fma_f32 v[0:1], v[28:29], v[14:15], v[0:1]
	s_add_i32 s16, s16, s10
	v_pk_fma_f32 v[2:3], v[10:11], v[48:49], v[2:3]
	v_pk_add_f32 v[0:1], v[6:7], v[0:1]
	v_pk_mul_f32 v[6:7], v[28:29], v[46:47]
	v_pk_mul_f32 v[10:11], v[10:11], v[50:51]
	s_ashr_i32 s17, s16, 31
	v_pk_fma_f32 v[6:7], v[30:31], v[14:15], v[6:7] neg_lo:[0,0,1] neg_hi:[0,0,1]
	v_pk_fma_f32 v[8:9], v[8:9], v[48:49], v[10:11] neg_lo:[0,0,1] neg_hi:[0,0,1]
	s_lshl_b64 s[16:17], s[16:17], 9
	v_pk_add_f32 v[4:5], v[4:5], v[6:7]
	v_pk_add_f32 v[6:7], v[12:13], v[8:9]
	v_lshl_add_u64 v[8:9], v[40:41], 0, s[16:17]
	v_pk_add_f32 v[54:55], v[96:97], v[54:55]
	v_pk_add_f32 v[62:63], v[80:81], v[62:63]
	v_pk_add_f32 v[18:19], v[32:33], v[18:19]
	v_pk_add_f32 v[2:3], v[44:45], v[2:3]
	global_store_dwordx4 v[8:9], v[20:23], off
	global_store_dwordx4 v[8:9], v[16:19], off offset:256
	global_store_dwordx4 v[8:9], v[66:69], off offset:64
	global_store_dwordx4 v[8:9], v[60:63], off offset:320
	global_store_dwordx4 v[8:9], v[56:59], off offset:128
	global_store_dwordx4 v[8:9], v[52:55], off offset:384
	global_store_dwordx4 v[8:9], v[4:7], off offset:192
	global_store_dwordx4 v[8:9], v[0:3], off offset:448
	s_branch .LBB0_520
